# v27 plus nt policy on other read-once loads: residual stream in C/K/N epilogues, gate pre-activations in J, x in P0
# baseline (speedup 1.0000x reference)
; #define GAS __attribute__((address_space(1)))
; __device__ __forceinline__ unsigned pk2(float lo, float hi) { unsigned r; asm("v_cvt_pk_bf16_f32 %0, %1, %2" : "=v"(r) : "v"(lo), "v"(hi)); return r; }
; #define IN(i) in_ptr(lds, (i))
; __device__ __forceinline__ void fix_row(float* hrow, bf16* hb, float* rout, int lane, const float* part, int nparts) {
;     f32x4 v[8]; float ss = 0.f;
; #pragma unroll
;     for (int j = 0; j < 8; ++j) v[j] = *(const f32x4*)(hrow + 4 * lane + 256 * j);
;     if (part != nullptr) {
;         for (int s = 0; s < nparts; ++s) {
; #pragma unroll
;             for (int j = 0; j < 8; ++j) v[j] = v[j] + *(const f32x4*)(part + (size_t)s * (256 * 2048) + 4 * lane + 256 * j); }
; #pragma unroll
;         for (int j = 0; j < 8; ++j) *(f32x4*)(hrow + 4 * lane + 256 * j) = v[j];
;     }
; #pragma unroll
;     for (int j = 0; j < 8; ++j) { ss += (v[j].x * v[j].x + v[j].y * v[j].y) + (v[j].z * v[j].z + v[j].w * v[j].w);
;         v2u w; w.x = pk2(v[j].x, v[j].y); w.y = pk2(v[j].z, v[j].w); *(v2u*)(hb + 4 * lane + 256 * j) = w; }
;     ss = wave_sum(ss, lane);
;     if (lane == 0) *rout = __builtin_amdgcn_rsqf(ss * (1.0f / D) + EPS);
; __global__ void __launch_bounds__(NWAVES * 64, 2) fwd(Args a) {
;     ...
;         for (int row = gw; row < M; row += NGW) { const int b = row >= LP ? 1 : 0, t = row - b * LP; float* hr = H + (size_t)row * D;
;             gfp src = t >= 128 ? IN(I_X) + (size_t)(b * SEQ + t - 128) * D : IN(I_META) + (size_t)(t >= PADR ? t - PADR : 0) * D;
; #pragma unroll
;             for (int j = 0; j < 8; ++j) { f32x4 v = *(const GAS f32x4*)(src + 4 * lane + 256 * j); if (t < PADR) v = (f32x4){0.f, 0.f, 0.f, 0.f}; *(f32x4*)(hr + 4 * lane + 256 * j) = v; }
;             fix_row(hr, HN + (size_t)row * D, RS + row, lane, nullptr, 0); }
.LBB0_20:
	s_lshl_b64 s[16:17], s[8:9], 13
	s_add_u32 s18, s18, s16
	s_addc_u32 s19, s19, s17
	s_nop 1
	global_load_dwordx4 v[10:13], v0, s[18:19] nt
	v_lshl_add_u64 v[18:19], s[0:1], 0, v[2:3]
	s_cmpk_lt_i32 s30, 0x70
	v_add_co_u32_e32 v42, vcc, s28, v18
	s_cselect_b64 s[16:17], -1, 0
	s_nop 0
	v_addc_co_u32_e32 v43, vcc, 0, v19, vcc
	v_add_co_u32_e32 v26, vcc, s26, v18
	v_lshl_add_u64 v[28:29], s[18:19], 0, v[0:1]
	s_nop 0
	v_addc_co_u32_e32 v27, vcc, 0, v19, vcc
	v_add_co_u32_e32 v38, vcc, s27, v28
	v_lshl_add_u64 v[44:45], s[0:1], 0, v[4:5]
	s_nop 0
	v_addc_co_u32_e32 v39, vcc, 0, v29, vcc
	v_add_co_u32_e32 v44, vcc, s29, v44
	global_load_dwordx4 v[60:63], v0, s[18:19] offset:1024 nt
	global_load_dwordx4 v[64:67], v0, s[18:19] offset:2048 nt
	global_load_dwordx4 v[68:71], v0, s[18:19] offset:3072 nt
	global_load_dwordx4 v[72:75], v[38:39], off nt
	global_load_dwordx4 v[76:79], v[38:39], off offset:1024 nt
	global_load_dwordx4 v[80:83], v[38:39], off offset:2048 nt
	global_load_dwordx4 v[84:87], v[38:39], off offset:3072 nt
	s_waitcnt vmcnt(7)
	v_cndmask_b32_e64 v13, v13, 0, s[16:17]
	v_cndmask_b32_e64 v12, v12, 0, s[16:17]
	v_cndmask_b32_e64 v11, v11, 0, s[16:17]
	v_cndmask_b32_e64 v10, v10, 0, s[16:17]
	global_store_dwordx4 v[42:43], v[10:13], off offset:-4096
	v_mul_f32_e32 v49, v13, v13
	v_mul_f32_e32 v48, v11, v11
	v_cvt_pk_bf16_f32 v46, v10, v11
	v_cvt_pk_bf16_f32 v47, v12, v13
	v_fmac_f32_e32 v49, v12, v12
	v_fmac_f32_e32 v48, v10, v10
	v_add_f32_e32 v10, v48, v49
	v_addc_co_u32_e32 v45, vcc, 0, v45, vcc
	s_waitcnt vmcnt(7)
	v_cndmask_b32_e64 v17, v63, 0, s[16:17]
	v_cndmask_b32_e64 v16, v62, 0, s[16:17]
	v_cndmask_b32_e64 v15, v61, 0, s[16:17]
	v_cndmask_b32_e64 v14, v60, 0, s[16:17]
	global_store_dwordx4 v[26:27], v[14:17], off offset:1024
	v_mul_f32_e32 v11, v15, v15
	v_mul_f32_e32 v12, v17, v17
	v_fmac_f32_e32 v11, v14, v14
	v_fmac_f32_e32 v12, v16, v16
	v_add_f32_e32 v11, v11, v12
	v_add_f32_e32 v10, v10, v11
	v_cvt_pk_bf16_f32 v49, v16, v17
	v_cvt_pk_bf16_f32 v48, v14, v15
	s_waitcnt vmcnt(7)
	v_cndmask_b32_e64 v21, v67, 0, s[16:17]
	v_cndmask_b32_e64 v20, v66, 0, s[16:17]
	v_cndmask_b32_e64 v19, v65, 0, s[16:17]
	v_cndmask_b32_e64 v18, v64, 0, s[16:17]
	global_store_dwordx4 v[26:27], v[18:21], off offset:2048
	v_mul_f32_e32 v11, v19, v19
	v_mul_f32_e32 v12, v21, v21
	v_fmac_f32_e32 v11, v18, v18
	v_fmac_f32_e32 v12, v20, v20
	v_add_f32_e32 v11, v11, v12
	v_add_f32_e32 v10, v10, v11
	v_cvt_pk_bf16_f32 v14, v18, v19
	v_cvt_pk_bf16_f32 v15, v20, v21
	s_waitcnt vmcnt(7)
	v_cndmask_b32_e64 v25, v71, 0, s[16:17]
	v_cndmask_b32_e64 v24, v70, 0, s[16:17]
	v_cndmask_b32_e64 v23, v69, 0, s[16:17]
	v_cndmask_b32_e64 v22, v68, 0, s[16:17]
	global_store_dwordx4 v[26:27], v[22:25], off offset:3072
	v_mul_f32_e32 v11, v23, v23
	v_mul_f32_e32 v12, v25, v25
	v_fmac_f32_e32 v11, v22, v22
	v_fmac_f32_e32 v12, v24, v24
	v_add_f32_e32 v11, v11, v12
	v_add_f32_e32 v10, v10, v11
	v_cvt_pk_bf16_f32 v16, v22, v23
	v_cvt_pk_bf16_f32 v17, v24, v25
	s_waitcnt vmcnt(7)
	v_cndmask_b32_e64 v29, v75, 0, s[16:17]
	v_cndmask_b32_e64 v28, v74, 0, s[16:17]
	v_cndmask_b32_e64 v27, v73, 0, s[16:17]
	v_cndmask_b32_e64 v26, v72, 0, s[16:17]
	global_store_dwordx4 v[42:43], v[26:29], off
	v_mul_f32_e32 v11, v27, v27
	v_mul_f32_e32 v12, v29, v29
	v_fmac_f32_e32 v11, v26, v26
	v_fmac_f32_e32 v12, v28, v28
	v_add_f32_e32 v11, v11, v12
	v_add_f32_e32 v10, v10, v11
	v_cvt_pk_bf16_f32 v18, v26, v27
	v_cvt_pk_bf16_f32 v19, v28, v29
	s_waitcnt vmcnt(7)
	v_cndmask_b32_e64 v33, v79, 0, s[16:17]
	v_cndmask_b32_e64 v32, v78, 0, s[16:17]
	v_cndmask_b32_e64 v31, v77, 0, s[16:17]
	v_cndmask_b32_e64 v30, v76, 0, s[16:17]
	global_store_dwordx4 v[42:43], v[30:33], off offset:1024
	v_mul_f32_e32 v11, v31, v31
	v_mul_f32_e32 v12, v33, v33
	v_fmac_f32_e32 v11, v30, v30
	v_fmac_f32_e32 v12, v32, v32
	v_add_f32_e32 v11, v11, v12
	v_add_f32_e32 v10, v10, v11
	v_cvt_pk_bf16_f32 v20, v30, v31
	v_cvt_pk_bf16_f32 v21, v32, v33
	s_waitcnt vmcnt(7)
	v_cndmask_b32_e64 v37, v83, 0, s[16:17]
	v_cndmask_b32_e64 v36, v82, 0, s[16:17]
	v_cndmask_b32_e64 v35, v81, 0, s[16:17]
	v_cndmask_b32_e64 v34, v80, 0, s[16:17]
	global_store_dwordx4 v[42:43], v[34:37], off offset:2048
	v_mul_f32_e32 v11, v35, v35
	v_mul_f32_e32 v12, v37, v37
	v_fmac_f32_e32 v11, v34, v34
	v_fmac_f32_e32 v12, v36, v36
	v_add_f32_e32 v11, v11, v12
	v_add_f32_e32 v24, v10, v11
	v_cvt_pk_bf16_f32 v22, v34, v35
	v_cvt_pk_bf16_f32 v23, v36, v37
	s_waitcnt vmcnt(7)
	v_cndmask_b32_e64 v13, v87, 0, s[16:17]
	v_cndmask_b32_e64 v12, v86, 0, s[16:17]
	v_cndmask_b32_e64 v11, v85, 0, s[16:17]
	v_cndmask_b32_e64 v10, v84, 0, s[16:17]
	global_store_dwordx4 v[42:43], v[10:13], off offset:3072
	global_store_dwordx2 v[44:45], v[46:47], off
	global_store_dwordx2 v[44:45], v[48:49], off offset:512
	global_store_dwordx2 v[44:45], v[14:15], off offset:1024
	global_store_dwordx2 v[44:45], v[16:17], off offset:1536
	global_store_dwordx2 v[44:45], v[18:19], off offset:2048
	global_store_dwordx2 v[44:45], v[20:21], off offset:2560
	global_store_dwordx2 v[44:45], v[22:23], off offset:3072
	v_mul_f32_e32 v16, v11, v11
	v_mul_f32_e32 v17, v13, v13
	v_fmac_f32_e32 v16, v10, v10
	v_fmac_f32_e32 v17, v12, v12
	v_cvt_pk_bf16_f32 v14, v10, v11
	v_add_f32_e32 v10, v16, v17
	v_add_f32_e32 v10, v24, v10
	v_cvt_pk_bf16_f32 v15, v12, v13
	global_store_dwordx2 v[44:45], v[14:15], off offset:3584
	s_nop 0
	v_add_f32_dpp v10, v10, v10 quad_perm:[1,0,3,2] row_mask:0xf bank_mask:0xf bound_ctrl:1
	s_nop 1
	v_add_f32_dpp v10, v10, v10 quad_perm:[2,3,0,1] row_mask:0xf bank_mask:0xf bound_ctrl:1
	s_nop 1
	v_add_f32_dpp v10, v10, v10 row_half_mirror row_mask:0xf bank_mask:0xf bound_ctrl:1
	s_nop 1
	v_add_f32_dpp v10, v10, v10 row_mirror row_mask:0xf bank_mask:0xf bound_ctrl:1
	v_mov_b32_e32 v11, v10
	s_nop 1
	v_permlane16_swap_b32 v10, v11
	s_nop 0
	v_add_f32_e32 v10, v10, v11
	v_mov_b32_e32 v11, v10
	s_nop 1
	v_permlane32_swap_b32 v10, v11
	s_and_saveexec_b64 s[16:17], s[4:5]
	s_cbranch_execz .LBB0_15
	v_add_f32_e32 v10, v10, v11
	v_fmamk_f32 v10, v10, 0x3a000000, v9
	v_rsq_f32_e32 v10, v10
	s_add_u32 s18, s0, s22
	s_addc_u32 s19, s1, s23
	global_store_dword v1, v10, s[18:19]
	s_branch .LBB0_15

; __device__ __forceinline__ unsigned cvt_pk_bf16(float lo, float hi) { unsigned r; asm volatile("v_cvt_pk_bf16_f32 %0, %1, %2" : "=v"(r) : "v"(lo), "v"(hi)); return r; }
;     __device__ __forceinline__ void operator()(const f32x4 (&acc)[2][2][4][2], const Unit& u, int wr, int wc, int fr, int fq) const {
;     ...
;             for (int m = 0; m < 4; ++m) { const int row = u.pm * BM + ai * HALF + wr * 64 + m * 16 + fr; const int b = row >= 4224 ? 1 : 0, t = row - b * 4224; float ss = 0.f;
; #pragma unroll
;                 for (int bj = 0; bj < 2; ++bj)
; #pragma unroll
;                     for (int n = 0; n < 2; ++n) { const int col = u.pn * BM + bj * HALF + wc * 32 + n * 16 + 4 * fq; float* p = H + (size_t)row * 2048 + col;
;                         const f32x4 v = *(const f32x4*)p + acc[ai][bj][m][n] * s; *(f32x4*)p = v;
;                         if (SSQ != nullptr) { typedef unsigned u32x2 __attribute__((ext_vector_type(2))); u32x2 w; w.x = cvt_pk_bf16(v[0], v[1]); w.y = cvt_pk_bf16(v[2], v[3]); *(u32x2*)(HB + (size_t)row * 2048 + col) = w;
;                             ss += (v[0] * v[0] + v[1] * v[1]) + (v[2] * v[2] + v[3] * v[3]); }
;                         if (OUT != 0ull && t >= 128) *(__attribute__((address_space(1))) f32x4*)(OUT + ((size_t)(b * 4096 + t - 128) * 2048 + col) * 4) = v; }
;                 if (SSQ != nullptr) {
;                     { float p0 = ss, p1 = ss; asm("s_nop 1\n\tv_permlane16_swap_b32 %0, %1" : "+v"(p0), "+v"(p1)); ss = p0 + p1; p0 = ss; p1 = ss; asm("s_nop 1\n\tv_permlane32_swap_b32 %0, %1" : "+v"(p0), "+v"(p1)); ss = p0 + p1; }
;                     if (fq == 0) SSQ[(size_t)row * 32 + 4 * u.pn + wc] = ss; }
.LBB0_359:
	s_add_i32 s0, s0, s41
	v_add_u32_e32 v138, s0, v141
	s_lshl_b32 s0, s48, 8
	s_or_b32 s0, s0, s42
	v_lshl_add_u32 v136, v140, 2, s0
	v_cmp_eq_u32_e32 vcc, 0, v140
	v_lshlrev_b32_e32 v164, 13, v138
	v_lshl_add_u32 v164, v136, 2, v164
	s_lshl_b32 s26, s48, 4
	s_lshl_b32 s0, s40, 2
	s_add_i32 s26, s26, s0
	v_lshl_add_u32 v165, v138, 7, s26
	global_load_dwordx4 v[182:185], v164, s[12:13] nt
	global_load_dwordx4 v[186:189], v164, s[12:13] offset:64 nt
	global_load_dwordx4 v[190:193], v164, s[12:13] offset:512 nt
	global_load_dwordx4 v[194:197], v164, s[12:13] offset:576 nt
	v_add_u32_e32 v242, 0x20000, v164
	global_load_dwordx4 v[198:201], v242, s[12:13] nt
	global_load_dwordx4 v[202:205], v242, s[12:13] offset:64 nt
	global_load_dwordx4 v[206:209], v242, s[12:13] offset:512 nt
	global_load_dwordx4 v[210:213], v242, s[12:13] offset:576 nt
	v_add_u32_e32 v242, 0x40000, v164
	global_load_dwordx4 v[214:217], v242, s[12:13] nt
	global_load_dwordx4 v[218:221], v242, s[12:13] offset:64 nt
	global_load_dwordx4 v[222:225], v242, s[12:13] offset:512 nt
	global_load_dwordx4 v[226:229], v242, s[12:13] offset:576 nt
	v_add_u32_e32 v242, 0x60000, v164
	global_load_dwordx4 v[148:151], v242, s[12:13] nt
	global_load_dwordx4 v[152:155], v242, s[12:13] offset:64 nt
	global_load_dwordx4 v[156:159], v242, s[12:13] offset:512 nt
	global_load_dwordx4 v[160:163], v242, s[12:13] offset:576 nt
	v_mov_b32_e32 v166, v164
	v_lshrrev_b32_e32 v167, 1, v166
	s_waitcnt vmcnt(12)
	v_pk_fma_f32 v[128:129], v[128:129], 0.5, v[184:185] op_sel_hi:[1,0,1]
	v_pk_fma_f32 v[126:127], v[126:127], 0.5, v[182:183] op_sel_hi:[1,0,1]
	global_store_dwordx4 v166, v[126:129], s[12:13]
	v_cvt_pk_bf16_f32 v142, v126, v127
	v_cvt_pk_bf16_f32 v143, v128, v129
	global_store_dwordx2 v167, v[142:143], s[14:15]
	v_mul_f32_e32 v168, v127, v127
	v_mul_f32_e32 v241, v129, v129
	v_fmac_f32_e32 v168, v126, v126
	v_fmac_f32_e32 v241, v128, v128
	v_add_f32_e32 v168, v168, v241
	v_pk_fma_f32 v[124:125], v[124:125], 0.5, v[188:189] op_sel_hi:[1,0,1]
	v_pk_fma_f32 v[122:123], v[122:123], 0.5, v[186:187] op_sel_hi:[1,0,1]
	global_store_dwordx4 v166, v[122:125], s[12:13] offset:64
	v_cvt_pk_bf16_f32 v142, v122, v123
	v_cvt_pk_bf16_f32 v143, v124, v125
	global_store_dwordx2 v167, v[142:143], s[14:15] offset:32
	v_mul_f32_e32 v240, v123, v123
	v_mul_f32_e32 v241, v125, v125
	v_fmac_f32_e32 v240, v122, v122
	v_fmac_f32_e32 v241, v124, v124
	v_add_f32_e32 v240, v240, v241
	v_add_f32_e32 v168, v168, v240
	v_pk_fma_f32 v[96:97], v[96:97], 0.5, v[192:193] op_sel_hi:[1,0,1]
	v_pk_fma_f32 v[94:95], v[94:95], 0.5, v[190:191] op_sel_hi:[1,0,1]
	global_store_dwordx4 v166, v[94:97], s[12:13] offset:512
	v_cvt_pk_bf16_f32 v142, v94, v95
	v_cvt_pk_bf16_f32 v143, v96, v97
	global_store_dwordx2 v167, v[142:143], s[14:15] offset:256
	v_mul_f32_e32 v240, v95, v95
	v_mul_f32_e32 v241, v97, v97
	v_fmac_f32_e32 v240, v94, v94
	v_fmac_f32_e32 v241, v96, v96
	v_add_f32_e32 v240, v240, v241
	v_add_f32_e32 v168, v168, v240
	v_pk_fma_f32 v[92:93], v[92:93], 0.5, v[196:197] op_sel_hi:[1,0,1]
	v_pk_fma_f32 v[90:91], v[90:91], 0.5, v[194:195] op_sel_hi:[1,0,1]
	global_store_dwordx4 v166, v[90:93], s[12:13] offset:576
	v_cvt_pk_bf16_f32 v142, v90, v91
	v_cvt_pk_bf16_f32 v143, v92, v93
	global_store_dwordx2 v167, v[142:143], s[14:15] offset:288
	v_mul_f32_e32 v240, v91, v91
	v_mul_f32_e32 v241, v93, v93
	v_fmac_f32_e32 v240, v90, v90
	v_fmac_f32_e32 v241, v92, v92
	v_add_f32_e32 v240, v240, v241
	v_add_f32_e32 v168, v168, v240
	v_add_u32_e32 v242, 0x100000, v164
	global_load_dwordx4 v[182:185], v242, s[12:13] nt
	global_load_dwordx4 v[186:189], v242, s[12:13] offset:64 nt
	global_load_dwordx4 v[190:193], v242, s[12:13] offset:512 nt
	global_load_dwordx4 v[194:197], v242, s[12:13] offset:576 nt
	v_mov_b32_e32 v169, v168
	s_nop 1
	v_permlane16_swap_b32 v168, v169
	s_nop 1
	v_add_f32_e32 v168, v168, v169
	v_mov_b32_e32 v169, v168
	s_nop 1
	v_permlane32_swap_b32 v169, v168
	v_mov_b32_e32 v243, v165
	s_and_saveexec_b64 s[8:9], vcc
	v_add_f32_e32 v244, v169, v168
	global_store_dword v243, v244, s[16:17]
	s_or_b64 exec, exec, s[8:9]
	v_add_u32_e32 v166, 0x20000, v164
	v_lshrrev_b32_e32 v167, 1, v166
	s_waitcnt vmcnt(21)
	v_pk_fma_f32 v[120:121], v[120:121], 0.5, v[200:201] op_sel_hi:[1,0,1]
	v_pk_fma_f32 v[118:119], v[118:119], 0.5, v[198:199] op_sel_hi:[1,0,1]
	global_store_dwordx4 v166, v[118:121], s[12:13]
	v_cvt_pk_bf16_f32 v142, v118, v119
	v_cvt_pk_bf16_f32 v143, v120, v121
	global_store_dwordx2 v167, v[142:143], s[14:15]
	v_mul_f32_e32 v168, v119, v119
	v_mul_f32_e32 v241, v121, v121
	v_fmac_f32_e32 v168, v118, v118
	v_fmac_f32_e32 v241, v120, v120
	v_add_f32_e32 v168, v168, v241
	v_pk_fma_f32 v[116:117], v[116:117], 0.5, v[204:205] op_sel_hi:[1,0,1]
	v_pk_fma_f32 v[114:115], v[114:115], 0.5, v[202:203] op_sel_hi:[1,0,1]
	global_store_dwordx4 v166, v[114:117], s[12:13] offset:64
	v_cvt_pk_bf16_f32 v142, v114, v115
	v_cvt_pk_bf16_f32 v143, v116, v117
	global_store_dwordx2 v167, v[142:143], s[14:15] offset:32
	v_mul_f32_e32 v240, v115, v115
	v_mul_f32_e32 v241, v117, v117
	v_fmac_f32_e32 v240, v114, v114
	v_fmac_f32_e32 v241, v116, v116
	v_add_f32_e32 v240, v240, v241
	v_add_f32_e32 v168, v168, v240
	v_pk_fma_f32 v[88:89], v[88:89], 0.5, v[208:209] op_sel_hi:[1,0,1]
	v_pk_fma_f32 v[86:87], v[86:87], 0.5, v[206:207] op_sel_hi:[1,0,1]
	global_store_dwordx4 v166, v[86:89], s[12:13] offset:512
	v_cvt_pk_bf16_f32 v142, v86, v87
	v_cvt_pk_bf16_f32 v143, v88, v89
	global_store_dwordx2 v167, v[142:143], s[14:15] offset:256
	v_mul_f32_e32 v240, v87, v87
	v_mul_f32_e32 v241, v89, v89
	v_fmac_f32_e32 v240, v86, v86
	v_fmac_f32_e32 v241, v88, v88
	v_add_f32_e32 v240, v240, v241
	v_add_f32_e32 v168, v168, v240
	v_pk_fma_f32 v[84:85], v[84:85], 0.5, v[212:213] op_sel_hi:[1,0,1]
	v_pk_fma_f32 v[82:83], v[82:83], 0.5, v[210:211] op_sel_hi:[1,0,1]
	global_store_dwordx4 v166, v[82:85], s[12:13] offset:576
	v_cvt_pk_bf16_f32 v142, v82, v83
	v_cvt_pk_bf16_f32 v143, v84, v85
	global_store_dwordx2 v167, v[142:143], s[14:15] offset:288
	v_mul_f32_e32 v240, v83, v83
	v_mul_f32_e32 v241, v85, v85
	v_fmac_f32_e32 v240, v82, v82
	v_fmac_f32_e32 v241, v84, v84
	v_add_f32_e32 v240, v240, v241
	v_add_f32_e32 v168, v168, v240
	v_add_u32_e32 v242, 0x120000, v164
	global_load_dwordx4 v[198:201], v242, s[12:13] nt
	global_load_dwordx4 v[202:205], v242, s[12:13] offset:64 nt
	global_load_dwordx4 v[206:209], v242, s[12:13] offset:512 nt
	global_load_dwordx4 v[210:213], v242, s[12:13] offset:576 nt
	v_mov_b32_e32 v169, v168
	s_nop 1
	v_permlane16_swap_b32 v168, v169
	s_nop 1
	v_add_f32_e32 v168, v168, v169
	v_mov_b32_e32 v169, v168
	s_nop 1
	v_permlane32_swap_b32 v169, v168
	v_add_u32_e32 v243, 0x800, v165
	s_and_saveexec_b64 s[8:9], vcc
	v_add_f32_e32 v244, v169, v168
	global_store_dword v243, v244, s[16:17]
	s_or_b64 exec, exec, s[8:9]
	v_add_u32_e32 v166, 0x40000, v164
	v_lshrrev_b32_e32 v167, 1, v166
	s_waitcnt vmcnt(30)
; __device__ __forceinline__ unsigned cvt_pk_bf16(float lo, float hi) { unsigned r; asm volatile("v_cvt_pk_bf16_f32 %0, %1, %2" : "=v"(r) : "v"(lo), "v"(hi)); return r; }
;     __device__ __forceinline__ void operator()(const f32x4 (&acc)[2][2][4][2], const Unit& u, int wr, int wc, int fr, int fq) const {
;     ...
;             for (int m = 0; m < 4; ++m) { const int row = u.pm * BM + ai * HALF + wr * 64 + m * 16 + fr; const int b = row >= 4224 ? 1 : 0, t = row - b * 4224; float ss = 0.f;
; #pragma unroll
;                 for (int bj = 0; bj < 2; ++bj)
; #pragma unroll
;                     for (int n = 0; n < 2; ++n) { const int col = u.pn * BM + bj * HALF + wc * 32 + n * 16 + 4 * fq; float* p = H + (size_t)row * 2048 + col;
;                         const f32x4 v = *(const f32x4*)p + acc[ai][bj][m][n] * s; *(f32x4*)p = v;
;                         if (SSQ != nullptr) { typedef unsigned u32x2 __attribute__((ext_vector_type(2))); u32x2 w; w.x = cvt_pk_bf16(v[0], v[1]); w.y = cvt_pk_bf16(v[2], v[3]); *(u32x2*)(HB + (size_t)row * 2048 + col) = w;
;                             ss += (v[0] * v[0] + v[1] * v[1]) + (v[2] * v[2] + v[3] * v[3]); }
;                         if (OUT != 0ull && t >= 128) *(__attribute__((address_space(1))) f32x4*)(OUT + ((size_t)(b * 4096 + t - 128) * 2048 + col) * 4) = v; }
;                 if (SSQ != nullptr) {
;                     { float p0 = ss, p1 = ss; asm("s_nop 1\n\tv_permlane16_swap_b32 %0, %1" : "+v"(p0), "+v"(p1)); ss = p0 + p1; p0 = ss; p1 = ss; asm("s_nop 1\n\tv_permlane32_swap_b32 %0, %1" : "+v"(p0), "+v"(p1)); ss = p0 + p1; }
;                     if (fq == 0) SSQ[(size_t)row * 32 + 4 * u.pn + wc] = ss; }
	v_pk_fma_f32 v[112:113], v[112:113], 0.5, v[216:217] op_sel_hi:[1,0,1]
	v_pk_fma_f32 v[110:111], v[110:111], 0.5, v[214:215] op_sel_hi:[1,0,1]
	global_store_dwordx4 v166, v[110:113], s[12:13]
	v_cvt_pk_bf16_f32 v142, v110, v111
	v_cvt_pk_bf16_f32 v143, v112, v113
	global_store_dwordx2 v167, v[142:143], s[14:15]
	v_mul_f32_e32 v168, v111, v111
	v_mul_f32_e32 v241, v113, v113
	v_fmac_f32_e32 v168, v110, v110
	v_fmac_f32_e32 v241, v112, v112
	v_add_f32_e32 v168, v168, v241
	v_pk_fma_f32 v[108:109], v[108:109], 0.5, v[220:221] op_sel_hi:[1,0,1]
	v_pk_fma_f32 v[106:107], v[106:107], 0.5, v[218:219] op_sel_hi:[1,0,1]
	global_store_dwordx4 v166, v[106:109], s[12:13] offset:64
	v_cvt_pk_bf16_f32 v142, v106, v107
	v_cvt_pk_bf16_f32 v143, v108, v109
	global_store_dwordx2 v167, v[142:143], s[14:15] offset:32
	v_mul_f32_e32 v240, v107, v107
	v_mul_f32_e32 v241, v109, v109
	v_fmac_f32_e32 v240, v106, v106
	v_fmac_f32_e32 v241, v108, v108
	v_add_f32_e32 v240, v240, v241
	v_add_f32_e32 v168, v168, v240
	v_pk_fma_f32 v[80:81], v[80:81], 0.5, v[224:225] op_sel_hi:[1,0,1]
	v_pk_fma_f32 v[78:79], v[78:79], 0.5, v[222:223] op_sel_hi:[1,0,1]
	global_store_dwordx4 v166, v[78:81], s[12:13] offset:512
	v_cvt_pk_bf16_f32 v142, v78, v79
	v_cvt_pk_bf16_f32 v143, v80, v81
	global_store_dwordx2 v167, v[142:143], s[14:15] offset:256
	v_mul_f32_e32 v240, v79, v79
	v_mul_f32_e32 v241, v81, v81
	v_fmac_f32_e32 v240, v78, v78
	v_fmac_f32_e32 v241, v80, v80
	v_add_f32_e32 v240, v240, v241
	v_add_f32_e32 v168, v168, v240
	v_pk_fma_f32 v[76:77], v[76:77], 0.5, v[228:229] op_sel_hi:[1,0,1]
	v_pk_fma_f32 v[74:75], v[74:75], 0.5, v[226:227] op_sel_hi:[1,0,1]
	global_store_dwordx4 v166, v[74:77], s[12:13] offset:576
	v_cvt_pk_bf16_f32 v142, v74, v75
	v_cvt_pk_bf16_f32 v143, v76, v77
	global_store_dwordx2 v167, v[142:143], s[14:15] offset:288
	v_mul_f32_e32 v240, v75, v75
	v_mul_f32_e32 v241, v77, v77
	v_fmac_f32_e32 v240, v74, v74
	v_fmac_f32_e32 v241, v76, v76
	v_add_f32_e32 v240, v240, v241
	v_add_f32_e32 v168, v168, v240
	v_add_u32_e32 v242, 0x140000, v164
	global_load_dwordx4 v[214:217], v242, s[12:13] nt
	global_load_dwordx4 v[218:221], v242, s[12:13] offset:64 nt
	global_load_dwordx4 v[222:225], v242, s[12:13] offset:512 nt
	global_load_dwordx4 v[226:229], v242, s[12:13] offset:576 nt
	v_mov_b32_e32 v169, v168
	s_nop 1
	v_permlane16_swap_b32 v168, v169
	s_nop 1
	v_add_f32_e32 v168, v168, v169
	v_mov_b32_e32 v169, v168
	s_nop 1
	v_permlane32_swap_b32 v169, v168
	v_add_u32_e32 v243, 0x1000, v165
	s_and_saveexec_b64 s[8:9], vcc
	v_add_f32_e32 v244, v169, v168
	global_store_dword v243, v244, s[16:17]
	s_or_b64 exec, exec, s[8:9]
	v_add_u32_e32 v166, 0x60000, v164
	v_lshrrev_b32_e32 v167, 1, v166
	s_waitcnt vmcnt(39)
	v_pk_fma_f32 v[104:105], v[104:105], 0.5, v[150:151] op_sel_hi:[1,0,1]
	v_pk_fma_f32 v[102:103], v[102:103], 0.5, v[148:149] op_sel_hi:[1,0,1]
	global_store_dwordx4 v166, v[102:105], s[12:13]
	v_cvt_pk_bf16_f32 v142, v102, v103
	v_cvt_pk_bf16_f32 v143, v104, v105
	global_store_dwordx2 v167, v[142:143], s[14:15]
	v_mul_f32_e32 v168, v103, v103
	v_mul_f32_e32 v241, v105, v105
	v_fmac_f32_e32 v168, v102, v102
	v_fmac_f32_e32 v241, v104, v104
	v_add_f32_e32 v168, v168, v241
	v_pk_fma_f32 v[100:101], v[100:101], 0.5, v[154:155] op_sel_hi:[1,0,1]
	v_pk_fma_f32 v[98:99], v[98:99], 0.5, v[152:153] op_sel_hi:[1,0,1]
	global_store_dwordx4 v166, v[98:101], s[12:13] offset:64
	v_cvt_pk_bf16_f32 v142, v98, v99
	v_cvt_pk_bf16_f32 v143, v100, v101
	global_store_dwordx2 v167, v[142:143], s[14:15] offset:32
	v_mul_f32_e32 v240, v99, v99
	v_mul_f32_e32 v241, v101, v101
	v_fmac_f32_e32 v240, v98, v98
	v_fmac_f32_e32 v241, v100, v100
	v_add_f32_e32 v240, v240, v241
	v_add_f32_e32 v168, v168, v240
	v_pk_fma_f32 v[72:73], v[72:73], 0.5, v[158:159] op_sel_hi:[1,0,1]
	v_pk_fma_f32 v[70:71], v[70:71], 0.5, v[156:157] op_sel_hi:[1,0,1]
	global_store_dwordx4 v166, v[70:73], s[12:13] offset:512
	v_cvt_pk_bf16_f32 v142, v70, v71
	v_cvt_pk_bf16_f32 v143, v72, v73
	global_store_dwordx2 v167, v[142:143], s[14:15] offset:256
	v_mul_f32_e32 v240, v71, v71
	v_mul_f32_e32 v241, v73, v73
	v_fmac_f32_e32 v240, v70, v70
	v_fmac_f32_e32 v241, v72, v72
	v_add_f32_e32 v240, v240, v241
	v_add_f32_e32 v168, v168, v240
	v_pk_fma_f32 v[68:69], v[68:69], 0.5, v[162:163] op_sel_hi:[1,0,1]
	v_pk_fma_f32 v[66:67], v[66:67], 0.5, v[160:161] op_sel_hi:[1,0,1]
	global_store_dwordx4 v166, v[66:69], s[12:13] offset:576
	v_cvt_pk_bf16_f32 v142, v66, v67
	v_cvt_pk_bf16_f32 v143, v68, v69
	global_store_dwordx2 v167, v[142:143], s[14:15] offset:288
	v_mul_f32_e32 v240, v67, v67
	v_mul_f32_e32 v241, v69, v69
	v_fmac_f32_e32 v240, v66, v66
	v_fmac_f32_e32 v241, v68, v68
	v_add_f32_e32 v240, v240, v241
	v_add_f32_e32 v168, v168, v240
	v_add_u32_e32 v242, 0x160000, v164
	global_load_dwordx4 v[148:151], v242, s[12:13] nt
	global_load_dwordx4 v[152:155], v242, s[12:13] offset:64 nt
	global_load_dwordx4 v[156:159], v242, s[12:13] offset:512 nt
	global_load_dwordx4 v[160:163], v242, s[12:13] offset:576 nt
	v_mov_b32_e32 v169, v168
	s_nop 1
	v_permlane16_swap_b32 v168, v169
	s_nop 1
	v_add_f32_e32 v168, v168, v169
	v_mov_b32_e32 v169, v168
	s_nop 1
	v_permlane32_swap_b32 v169, v168
	v_add_u32_e32 v243, 0x1800, v165
	s_and_saveexec_b64 s[8:9], vcc
	v_add_f32_e32 v244, v169, v168
	global_store_dword v243, v244, s[16:17]
	s_or_b64 exec, exec, s[8:9]
	v_add_u32_e32 v166, 0x100000, v164
	v_lshrrev_b32_e32 v167, 1, v166
	s_waitcnt vmcnt(40)
; __device__ __forceinline__ unsigned cvt_pk_bf16(float lo, float hi) { unsigned r; asm volatile("v_cvt_pk_bf16_f32 %0, %1, %2" : "=v"(r) : "v"(lo), "v"(hi)); return r; }
;     __device__ __forceinline__ void operator()(const f32x4 (&acc)[2][2][4][2], const Unit& u, int wr, int wc, int fr, int fq) const {
;     ...
;             for (int m = 0; m < 4; ++m) { const int row = u.pm * BM + ai * HALF + wr * 64 + m * 16 + fr; const int b = row >= 4224 ? 1 : 0, t = row - b * 4224; float ss = 0.f;
; #pragma unroll
;                 for (int bj = 0; bj < 2; ++bj)
; #pragma unroll
;                     for (int n = 0; n < 2; ++n) { const int col = u.pn * BM + bj * HALF + wc * 32 + n * 16 + 4 * fq; float* p = H + (size_t)row * 2048 + col;
;                         const f32x4 v = *(const f32x4*)p + acc[ai][bj][m][n] * s; *(f32x4*)p = v;
;                         if (SSQ != nullptr) { typedef unsigned u32x2 __attribute__((ext_vector_type(2))); u32x2 w; w.x = cvt_pk_bf16(v[0], v[1]); w.y = cvt_pk_bf16(v[2], v[3]); *(u32x2*)(HB + (size_t)row * 2048 + col) = w;
;                             ss += (v[0] * v[0] + v[1] * v[1]) + (v[2] * v[2] + v[3] * v[3]); }
;                         if (OUT != 0ull && t >= 128) *(__attribute__((address_space(1))) f32x4*)(OUT + ((size_t)(b * 4096 + t - 128) * 2048 + col) * 4) = v; }
;                 if (SSQ != nullptr) {
;                     { float p0 = ss, p1 = ss; asm("s_nop 1\n\tv_permlane16_swap_b32 %0, %1" : "+v"(p0), "+v"(p1)); ss = p0 + p1; p0 = ss; p1 = ss; asm("s_nop 1\n\tv_permlane32_swap_b32 %0, %1" : "+v"(p0), "+v"(p1)); ss = p0 + p1; }
;                     if (fq == 0) SSQ[(size_t)row * 32 + 4 * u.pn + wc] = ss; }
	v_pk_fma_f32 v[64:65], v[64:65], 0.5, v[184:185] op_sel_hi:[1,0,1]
	v_pk_fma_f32 v[62:63], v[62:63], 0.5, v[182:183] op_sel_hi:[1,0,1]
	global_store_dwordx4 v166, v[62:65], s[12:13]
	v_cvt_pk_bf16_f32 v142, v62, v63
	v_cvt_pk_bf16_f32 v143, v64, v65
	global_store_dwordx2 v167, v[142:143], s[14:15]
	v_mul_f32_e32 v168, v63, v63
	v_mul_f32_e32 v241, v65, v65
	v_fmac_f32_e32 v168, v62, v62
	v_fmac_f32_e32 v241, v64, v64
	v_add_f32_e32 v168, v168, v241
	v_pk_fma_f32 v[60:61], v[60:61], 0.5, v[188:189] op_sel_hi:[1,0,1]
	v_pk_fma_f32 v[58:59], v[58:59], 0.5, v[186:187] op_sel_hi:[1,0,1]
	global_store_dwordx4 v166, v[58:61], s[12:13] offset:64
	v_cvt_pk_bf16_f32 v142, v58, v59
	v_cvt_pk_bf16_f32 v143, v60, v61
	global_store_dwordx2 v167, v[142:143], s[14:15] offset:32
	v_mul_f32_e32 v240, v59, v59
	v_mul_f32_e32 v241, v61, v61
	v_fmac_f32_e32 v240, v58, v58
	v_fmac_f32_e32 v241, v60, v60
	v_add_f32_e32 v240, v240, v241
	v_add_f32_e32 v168, v168, v240
	v_pk_fma_f32 v[32:33], v[32:33], 0.5, v[192:193] op_sel_hi:[1,0,1]
	v_pk_fma_f32 v[30:31], v[30:31], 0.5, v[190:191] op_sel_hi:[1,0,1]
	global_store_dwordx4 v166, v[30:33], s[12:13] offset:512
	v_cvt_pk_bf16_f32 v142, v30, v31
	v_cvt_pk_bf16_f32 v143, v32, v33
	global_store_dwordx2 v167, v[142:143], s[14:15] offset:256
	v_mul_f32_e32 v240, v31, v31
	v_mul_f32_e32 v241, v33, v33
	v_fmac_f32_e32 v240, v30, v30
	v_fmac_f32_e32 v241, v32, v32
	v_add_f32_e32 v240, v240, v241
	v_add_f32_e32 v168, v168, v240
	v_pk_fma_f32 v[28:29], v[28:29], 0.5, v[196:197] op_sel_hi:[1,0,1]
	v_pk_fma_f32 v[26:27], v[26:27], 0.5, v[194:195] op_sel_hi:[1,0,1]
	global_store_dwordx4 v166, v[26:29], s[12:13] offset:576
	v_cvt_pk_bf16_f32 v142, v26, v27
	v_cvt_pk_bf16_f32 v143, v28, v29
	global_store_dwordx2 v167, v[142:143], s[14:15] offset:288
	v_mul_f32_e32 v240, v27, v27
	v_mul_f32_e32 v241, v29, v29
	v_fmac_f32_e32 v240, v26, v26
	v_fmac_f32_e32 v241, v28, v28
	v_add_f32_e32 v240, v240, v241
	v_add_f32_e32 v168, v168, v240
	v_mov_b32_e32 v169, v168
	s_nop 1
	v_permlane16_swap_b32 v168, v169
	s_nop 1
	v_add_f32_e32 v168, v168, v169
	v_mov_b32_e32 v169, v168
	s_nop 1
	v_permlane32_swap_b32 v169, v168
	v_add_u32_e32 v243, 0x4000, v165
	s_and_saveexec_b64 s[8:9], vcc
	v_add_f32_e32 v244, v169, v168
	global_store_dword v243, v244, s[16:17]
	s_or_b64 exec, exec, s[8:9]
	v_add_u32_e32 v166, 0x120000, v164
	v_lshrrev_b32_e32 v167, 1, v166
	s_waitcnt vmcnt(36)
	v_pk_fma_f32 v[56:57], v[56:57], 0.5, v[200:201] op_sel_hi:[1,0,1]
	v_pk_fma_f32 v[54:55], v[54:55], 0.5, v[198:199] op_sel_hi:[1,0,1]
	global_store_dwordx4 v166, v[54:57], s[12:13]
	v_cvt_pk_bf16_f32 v142, v54, v55
	v_cvt_pk_bf16_f32 v143, v56, v57
	global_store_dwordx2 v167, v[142:143], s[14:15]
	v_mul_f32_e32 v168, v55, v55
	v_mul_f32_e32 v241, v57, v57
	v_fmac_f32_e32 v168, v54, v54
	v_fmac_f32_e32 v241, v56, v56
	v_add_f32_e32 v168, v168, v241
	v_pk_fma_f32 v[52:53], v[52:53], 0.5, v[204:205] op_sel_hi:[1,0,1]
	v_pk_fma_f32 v[50:51], v[50:51], 0.5, v[202:203] op_sel_hi:[1,0,1]
	global_store_dwordx4 v166, v[50:53], s[12:13] offset:64
	v_cvt_pk_bf16_f32 v142, v50, v51
	v_cvt_pk_bf16_f32 v143, v52, v53
	global_store_dwordx2 v167, v[142:143], s[14:15] offset:32
	v_mul_f32_e32 v240, v51, v51
	v_mul_f32_e32 v241, v53, v53
	v_fmac_f32_e32 v240, v50, v50
	v_fmac_f32_e32 v241, v52, v52
	v_add_f32_e32 v240, v240, v241
	v_add_f32_e32 v168, v168, v240
	v_pk_fma_f32 v[24:25], v[24:25], 0.5, v[208:209] op_sel_hi:[1,0,1]
	v_pk_fma_f32 v[22:23], v[22:23], 0.5, v[206:207] op_sel_hi:[1,0,1]
	global_store_dwordx4 v166, v[22:25], s[12:13] offset:512
	v_cvt_pk_bf16_f32 v142, v22, v23
	v_cvt_pk_bf16_f32 v143, v24, v25
	global_store_dwordx2 v167, v[142:143], s[14:15] offset:256
	v_mul_f32_e32 v240, v23, v23
	v_mul_f32_e32 v241, v25, v25
	v_fmac_f32_e32 v240, v22, v22
	v_fmac_f32_e32 v241, v24, v24
	v_add_f32_e32 v240, v240, v241
	v_add_f32_e32 v168, v168, v240
	v_pk_fma_f32 v[20:21], v[20:21], 0.5, v[212:213] op_sel_hi:[1,0,1]
	v_pk_fma_f32 v[18:19], v[18:19], 0.5, v[210:211] op_sel_hi:[1,0,1]
	global_store_dwordx4 v166, v[18:21], s[12:13] offset:576
	v_cvt_pk_bf16_f32 v142, v18, v19
	v_cvt_pk_bf16_f32 v143, v20, v21
	global_store_dwordx2 v167, v[142:143], s[14:15] offset:288
	v_mul_f32_e32 v240, v19, v19
	v_mul_f32_e32 v241, v21, v21
	v_fmac_f32_e32 v240, v18, v18
	v_fmac_f32_e32 v241, v20, v20
	v_add_f32_e32 v240, v240, v241
	v_add_f32_e32 v168, v168, v240
	v_mov_b32_e32 v169, v168
	s_nop 1
	v_permlane16_swap_b32 v168, v169
	s_nop 1
	v_add_f32_e32 v168, v168, v169
	v_mov_b32_e32 v169, v168
	s_nop 1
	v_permlane32_swap_b32 v169, v168
	v_add_u32_e32 v243, 0x4800, v165
	s_and_saveexec_b64 s[8:9], vcc
	v_add_f32_e32 v244, v169, v168
	global_store_dword v243, v244, s[16:17]
	s_or_b64 exec, exec, s[8:9]
	v_add_u32_e32 v166, 0x140000, v164
	v_lshrrev_b32_e32 v167, 1, v166
	s_waitcnt vmcnt(32)
; __device__ __forceinline__ unsigned cvt_pk_bf16(float lo, float hi) { unsigned r; asm volatile("v_cvt_pk_bf16_f32 %0, %1, %2" : "=v"(r) : "v"(lo), "v"(hi)); return r; }
;     __device__ __forceinline__ void operator()(const f32x4 (&acc)[2][2][4][2], const Unit& u, int wr, int wc, int fr, int fq) const {
;     ...
;             for (int m = 0; m < 4; ++m) { const int row = u.pm * BM + ai * HALF + wr * 64 + m * 16 + fr; const int b = row >= 4224 ? 1 : 0, t = row - b * 4224; float ss = 0.f;
; #pragma unroll
;                 for (int bj = 0; bj < 2; ++bj)
; #pragma unroll
;                     for (int n = 0; n < 2; ++n) { const int col = u.pn * BM + bj * HALF + wc * 32 + n * 16 + 4 * fq; float* p = H + (size_t)row * 2048 + col;
;                         const f32x4 v = *(const f32x4*)p + acc[ai][bj][m][n] * s; *(f32x4*)p = v;
;                         if (SSQ != nullptr) { typedef unsigned u32x2 __attribute__((ext_vector_type(2))); u32x2 w; w.x = cvt_pk_bf16(v[0], v[1]); w.y = cvt_pk_bf16(v[2], v[3]); *(u32x2*)(HB + (size_t)row * 2048 + col) = w;
;                             ss += (v[0] * v[0] + v[1] * v[1]) + (v[2] * v[2] + v[3] * v[3]); }
;                         if (OUT != 0ull && t >= 128) *(__attribute__((address_space(1))) f32x4*)(OUT + ((size_t)(b * 4096 + t - 128) * 2048 + col) * 4) = v; }
;                 if (SSQ != nullptr) {
;                     { float p0 = ss, p1 = ss; asm("s_nop 1\n\tv_permlane16_swap_b32 %0, %1" : "+v"(p0), "+v"(p1)); ss = p0 + p1; p0 = ss; p1 = ss; asm("s_nop 1\n\tv_permlane32_swap_b32 %0, %1" : "+v"(p0), "+v"(p1)); ss = p0 + p1; }
;                     if (fq == 0) SSQ[(size_t)row * 32 + 4 * u.pn + wc] = ss; }
	v_pk_fma_f32 v[48:49], v[48:49], 0.5, v[216:217] op_sel_hi:[1,0,1]
	v_pk_fma_f32 v[46:47], v[46:47], 0.5, v[214:215] op_sel_hi:[1,0,1]
	global_store_dwordx4 v166, v[46:49], s[12:13]
	v_cvt_pk_bf16_f32 v142, v46, v47
	v_cvt_pk_bf16_f32 v143, v48, v49
	global_store_dwordx2 v167, v[142:143], s[14:15]
	v_mul_f32_e32 v168, v47, v47
	v_mul_f32_e32 v241, v49, v49
	v_fmac_f32_e32 v168, v46, v46
	v_fmac_f32_e32 v241, v48, v48
	v_add_f32_e32 v168, v168, v241
	v_pk_fma_f32 v[44:45], v[44:45], 0.5, v[220:221] op_sel_hi:[1,0,1]
	v_pk_fma_f32 v[42:43], v[42:43], 0.5, v[218:219] op_sel_hi:[1,0,1]
	global_store_dwordx4 v166, v[42:45], s[12:13] offset:64
	v_cvt_pk_bf16_f32 v142, v42, v43
	v_cvt_pk_bf16_f32 v143, v44, v45
	global_store_dwordx2 v167, v[142:143], s[14:15] offset:32
	v_mul_f32_e32 v240, v43, v43
	v_mul_f32_e32 v241, v45, v45
	v_fmac_f32_e32 v240, v42, v42
	v_fmac_f32_e32 v241, v44, v44
	v_add_f32_e32 v240, v240, v241
	v_add_f32_e32 v168, v168, v240
	v_pk_fma_f32 v[16:17], v[16:17], 0.5, v[224:225] op_sel_hi:[1,0,1]
	v_pk_fma_f32 v[14:15], v[14:15], 0.5, v[222:223] op_sel_hi:[1,0,1]
	global_store_dwordx4 v166, v[14:17], s[12:13] offset:512
	v_cvt_pk_bf16_f32 v142, v14, v15
	v_cvt_pk_bf16_f32 v143, v16, v17
	global_store_dwordx2 v167, v[142:143], s[14:15] offset:256
	v_mul_f32_e32 v240, v15, v15
	v_mul_f32_e32 v241, v17, v17
	v_fmac_f32_e32 v240, v14, v14
	v_fmac_f32_e32 v241, v16, v16
	v_add_f32_e32 v240, v240, v241
	v_add_f32_e32 v168, v168, v240
	v_pk_fma_f32 v[12:13], v[12:13], 0.5, v[228:229] op_sel_hi:[1,0,1]
	v_pk_fma_f32 v[10:11], v[10:11], 0.5, v[226:227] op_sel_hi:[1,0,1]
	global_store_dwordx4 v166, v[10:13], s[12:13] offset:576
	v_cvt_pk_bf16_f32 v142, v10, v11
	v_cvt_pk_bf16_f32 v143, v12, v13
	global_store_dwordx2 v167, v[142:143], s[14:15] offset:288
	v_mul_f32_e32 v240, v11, v11
	v_mul_f32_e32 v241, v13, v13
	v_fmac_f32_e32 v240, v10, v10
	v_fmac_f32_e32 v241, v12, v12
	v_add_f32_e32 v240, v240, v241
	v_add_f32_e32 v168, v168, v240
	v_mov_b32_e32 v169, v168
	s_nop 1
	v_permlane16_swap_b32 v168, v169
	s_nop 1
	v_add_f32_e32 v168, v168, v169
	v_mov_b32_e32 v169, v168
	s_nop 1
	v_permlane32_swap_b32 v169, v168
	v_add_u32_e32 v243, 0x5000, v165
	s_and_saveexec_b64 s[8:9], vcc
	v_add_f32_e32 v244, v169, v168
	global_store_dword v243, v244, s[16:17]
	s_or_b64 exec, exec, s[8:9]
	v_add_u32_e32 v166, 0x160000, v164
	v_lshrrev_b32_e32 v167, 1, v166
	s_waitcnt vmcnt(28)
	v_pk_fma_f32 v[40:41], v[40:41], 0.5, v[150:151] op_sel_hi:[1,0,1]
	v_pk_fma_f32 v[38:39], v[38:39], 0.5, v[148:149] op_sel_hi:[1,0,1]
	global_store_dwordx4 v166, v[38:41], s[12:13]
	v_cvt_pk_bf16_f32 v142, v38, v39
	v_cvt_pk_bf16_f32 v143, v40, v41
	global_store_dwordx2 v167, v[142:143], s[14:15]
	v_mul_f32_e32 v168, v39, v39
	v_mul_f32_e32 v241, v41, v41
	v_fmac_f32_e32 v168, v38, v38
	v_fmac_f32_e32 v241, v40, v40
	v_add_f32_e32 v168, v168, v241
	v_pk_fma_f32 v[36:37], v[36:37], 0.5, v[154:155] op_sel_hi:[1,0,1]
	v_pk_fma_f32 v[34:35], v[34:35], 0.5, v[152:153] op_sel_hi:[1,0,1]
	global_store_dwordx4 v166, v[34:37], s[12:13] offset:64
	v_cvt_pk_bf16_f32 v142, v34, v35
	v_cvt_pk_bf16_f32 v143, v36, v37
	global_store_dwordx2 v167, v[142:143], s[14:15] offset:32
	v_mul_f32_e32 v240, v35, v35
	v_mul_f32_e32 v241, v37, v37
	v_fmac_f32_e32 v240, v34, v34
	v_fmac_f32_e32 v241, v36, v36
	v_add_f32_e32 v240, v240, v241
	v_add_f32_e32 v168, v168, v240
	v_pk_fma_f32 v[8:9], v[8:9], 0.5, v[158:159] op_sel_hi:[1,0,1]
	v_pk_fma_f32 v[6:7], v[6:7], 0.5, v[156:157] op_sel_hi:[1,0,1]
	global_store_dwordx4 v166, v[6:9], s[12:13] offset:512
	v_cvt_pk_bf16_f32 v142, v6, v7
	v_cvt_pk_bf16_f32 v143, v8, v9
	global_store_dwordx2 v167, v[142:143], s[14:15] offset:256
	v_mul_f32_e32 v240, v7, v7
	v_mul_f32_e32 v241, v9, v9
	v_fmac_f32_e32 v240, v6, v6
	v_fmac_f32_e32 v241, v8, v8
	v_add_f32_e32 v240, v240, v241
	v_add_f32_e32 v168, v168, v240
	v_pk_fma_f32 v[4:5], v[4:5], 0.5, v[162:163] op_sel_hi:[1,0,1]
	v_pk_fma_f32 v[2:3], v[2:3], 0.5, v[160:161] op_sel_hi:[1,0,1]
	global_store_dwordx4 v166, v[2:5], s[12:13] offset:576
	v_cvt_pk_bf16_f32 v142, v2, v3
	v_cvt_pk_bf16_f32 v143, v4, v5
	global_store_dwordx2 v167, v[142:143], s[14:15] offset:288
	v_mul_f32_e32 v240, v3, v3
	v_mul_f32_e32 v241, v5, v5
	v_fmac_f32_e32 v240, v2, v2
	v_fmac_f32_e32 v241, v4, v4
	v_add_f32_e32 v240, v240, v241
	v_add_f32_e32 v168, v168, v240
	v_mov_b32_e32 v169, v168
	s_nop 1
	v_permlane16_swap_b32 v168, v169
	s_nop 1
	v_add_f32_e32 v168, v168, v169
	v_mov_b32_e32 v169, v168
	s_nop 1
	v_permlane32_swap_b32 v169, v168
	v_add_u32_e32 v243, 0x5800, v165
	s_and_saveexec_b64 s[8:9], vcc
	v_add_f32_e32 v244, v169, v168
	global_store_dword v243, v244, s[16:17]
	s_or_b64 exec, exec, s[8:9]
	s_andn2_b64 vcc, exec, s[24:25]
	s_mov_b64 s[8:9], -1
	s_cbranch_vccnz .LBB0_347

;     __device__ __forceinline__ void operator()(f32x4 (&acc)[2][2][4][2], const Unit& u, int wr, int wc, int fr, int fq) const {
;     ...
;         const bool tail = (u.tag & 0x200) != 0; const int br = tail ? ((u.tag & 0xff) >> 2) : (u.tag & 3);
;         float* pb = PART + (size_t)(u.tag & 0xff) * (256 * 2048);
;         const bool resc = !tail && br < 2;
; #pragma unroll
;         for (int ai = 0; ai < 2; ++ai) {
;             u32x2 gaa[4][2][2], gbb[4][2][2];
; #pragma unroll
;             for (int m = 0; m < 4; ++m)
; #pragma unroll
;                 for (int bj = 0; bj < 2; ++bj)
; #pragma unroll
;                     for (int n = 0; n < 2; ++n) { const bf16_t* gp = G + (size_t)(u.pm * BM + ai * HALF + wr * 64 + m * 16 + fr) * ldg + br * 2048 + u.pn * BM + bj * HALF + wc * 32 + n * 16 + 4 * fq;
;                         gaa[m][bj][n] = *(const u32x2*)gp; if (resc) gbb[m][bj][n] = *(const u32x2*)(gp + 2048); }
.LBB0_903:
	s_and_b32 s10, s34, 0x200
	s_bitcmp1_b32 s34, 9
	s_cselect_b64 s[8:9], -1, 0
	s_bfe_u32 s14, s34, 0x60002
	s_and_b32 s30, s34, 3
	s_cmp_eq_u32 s10, 0
	s_cselect_b64 s[10:11], -1, 0
	s_and_b64 s[12:13], s[10:11], exec
	s_cselect_b32 s14, s30, s14
	s_cmp_lt_u32 s14, 2
	s_cselect_b64 s[12:13], -1, 0
	s_and_b64 s[30:31], s[10:11], s[12:13]
	s_xor_b64 s[10:11], s[30:31], -1
	s_lshl_b32 s68, s35, 8
	s_lshl_b32 s12, s14, 12
	s_add_u32 s35, s41, s12
	s_addc_u32 s46, s42, 0
	s_lshl_b32 s12, s15, 8
	s_ashr_i32 s13, s12, 31
	s_lshl_b64 s[14:15], s[12:13], 1
	s_add_u32 s13, s35, s14
	v_mov_b32_e32 v0, v241
	v_mov_b32_e32 v2, v240
	s_addc_u32 s15, s46, s15
	s_add_u32 s14, s13, s33
	v_lshlrev_b32_e32 v132, 2, v0
	v_add_u32_e32 v148, s45, v2
	v_ashrrev_i32_e32 v133, 31, v132
	s_addc_u32 s15, s15, 0
	v_add_u32_e32 v144, s68, v148
	v_lshl_add_u64 v[190:191], v[132:133], 1, s[14:15]
	v_mad_i64_i32 v[2:3], s[14:15], v144, s71, v[190:191]
	global_load_dwordx2 v[134:135], v[2:3], off nt
	s_and_b64 vcc, exec, s[10:11]
	s_cbranch_vccnz .LBB0_905
	v_add_co_u32_e32 v146, vcc, 0x1000, v2
	s_nop 1
	v_addc_co_u32_e32 v147, vcc, 0, v3, vcc
	global_load_dwordx2 v[188:189], v[146:147], off nt
.LBB0_905:
	global_load_dwordx2 v[224:225], v[2:3], off offset:32 nt
	v_cndmask_b32_e64 v0, 0, 1, s[30:31]
	v_cmp_ne_u32_e64 s[14:15], 1, v0
	s_andn2_b64 vcc, exec, s[30:31]
	s_cbranch_vccnz .LBB0_907
	v_add_co_u32_e32 v146, vcc, 0x1000, v2
	s_nop 1
	v_addc_co_u32_e32 v147, vcc, 0, v3, vcc
	global_load_dwordx2 v[186:187], v[146:147], off offset:32 nt
.LBB0_907:
	global_load_dwordx2 v[218:219], v[2:3], off offset:256 nt
	s_and_b64 vcc, exec, s[14:15]
	s_movk_i32 s95, 0x1fff
	s_cbranch_vccnz .LBB0_909
	v_add_co_u32_e32 v146, vcc, 0x1000, v2
	s_nop 1
	v_addc_co_u32_e32 v147, vcc, 0, v3, vcc
	global_load_dwordx2 v[184:185], v[146:147], off offset:256 nt
	global_load_dwordx2 v[216:217], v[2:3], off offset:288 nt
	s_and_b64 vcc, exec, s[14:15]
	s_cbranch_vccz .LBB0_910
	s_branch .LBB0_911
.LBB0_909:
	global_load_dwordx2 v[216:217], v[2:3], off offset:288 nt
	s_and_b64 vcc, exec, s[14:15]
	s_cbranch_vccnz .LBB0_911
.LBB0_910:
	v_add_co_u32_e32 v2, vcc, 0x1000, v2
	s_nop 1
	v_addc_co_u32_e32 v3, vcc, 0, v3, vcc
	global_load_dwordx2 v[182:183], v[2:3], off offset:288 nt
.LBB0_911:
	v_add_u32_e32 v0, 16, v144
	v_mad_i64_i32 v[2:3], s[30:31], v0, s71, v[190:191]
	global_load_dwordx2 v[214:215], v[2:3], off nt
	s_and_b64 vcc, exec, s[14:15]
	v_ashrrev_i32_e32 v145, 31, v144
	s_cbranch_vccnz .LBB0_915
	v_add_co_u32_e32 v146, vcc, 0x1000, v2
	s_nop 1
	v_addc_co_u32_e32 v147, vcc, 0, v3, vcc
	global_load_dwordx2 v[168:169], v[146:147], off nt
	global_load_dwordx2 v[212:213], v[2:3], off offset:32 nt
	s_and_b64 vcc, exec, s[14:15]
	s_cbranch_vccz .LBB0_916
.LBB0_913:
	global_load_dwordx2 v[210:211], v[2:3], off offset:256 nt
	s_and_b64 vcc, exec, s[14:15]
	s_cbranch_vccnz .LBB0_917
.LBB0_914:
	v_add_co_u32_e32 v146, vcc, 0x1000, v2
	s_nop 1
	v_addc_co_u32_e32 v147, vcc, 0, v3, vcc
	global_load_dwordx2 v[164:165], v[146:147], off offset:256 nt
	global_load_dwordx2 v[208:209], v[2:3], off offset:288 nt
	s_and_b64 vcc, exec, s[14:15]
	s_cbranch_vccz .LBB0_918
	s_branch .LBB0_919
.LBB0_915:
	global_load_dwordx2 v[212:213], v[2:3], off offset:32 nt
	s_and_b64 vcc, exec, s[14:15]
	s_cbranch_vccnz .LBB0_913
.LBB0_916:
	v_add_co_u32_e32 v146, vcc, 0x1000, v2
	s_nop 1
	v_addc_co_u32_e32 v147, vcc, 0, v3, vcc
	global_load_dwordx2 v[166:167], v[146:147], off offset:32 nt
	global_load_dwordx2 v[210:211], v[2:3], off offset:256 nt
	s_and_b64 vcc, exec, s[14:15]
	s_cbranch_vccz .LBB0_914
.LBB0_917:
	global_load_dwordx2 v[208:209], v[2:3], off offset:288 nt
	s_and_b64 vcc, exec, s[14:15]
	s_cbranch_vccnz .LBB0_919
.LBB0_918:
	v_add_co_u32_e32 v2, vcc, 0x1000, v2
	s_nop 1
	v_addc_co_u32_e32 v3, vcc, 0, v3, vcc
	global_load_dwordx2 v[162:163], v[2:3], off offset:288 nt
.LBB0_919:
	v_add_u32_e32 v0, 32, v144
	v_mad_i64_i32 v[2:3], s[30:31], v0, s71, v[190:191]
	global_load_dwordx2 v[206:207], v[2:3], off nt
	s_and_b64 vcc, exec, s[14:15]
	s_cbranch_vccnz .LBB0_923
	v_add_co_u32_e32 v146, vcc, 0x1000, v2
	s_nop 1
	v_addc_co_u32_e32 v147, vcc, 0, v3, vcc
	global_load_dwordx2 v[160:161], v[146:147], off nt
	global_load_dwordx2 v[204:205], v[2:3], off offset:32 nt
	s_and_b64 vcc, exec, s[14:15]
	s_cbranch_vccz .LBB0_924
.LBB0_921:
	global_load_dwordx2 v[202:203], v[2:3], off offset:256 nt
	s_and_b64 vcc, exec, s[14:15]
	s_cbranch_vccnz .LBB0_925
.LBB0_922:
	v_add_co_u32_e32 v146, vcc, 0x1000, v2
	s_nop 1
	v_addc_co_u32_e32 v147, vcc, 0, v3, vcc
	global_load_dwordx2 v[156:157], v[146:147], off offset:256 nt
	global_load_dwordx2 v[200:201], v[2:3], off offset:288 nt
	s_and_b64 vcc, exec, s[14:15]
	s_cbranch_vccz .LBB0_926
	s_branch .LBB0_927
.LBB0_923:
	global_load_dwordx2 v[204:205], v[2:3], off offset:32 nt
	s_and_b64 vcc, exec, s[14:15]
	s_cbranch_vccnz .LBB0_921
.LBB0_924:
	v_add_co_u32_e32 v146, vcc, 0x1000, v2
	s_nop 1
	v_addc_co_u32_e32 v147, vcc, 0, v3, vcc
	global_load_dwordx2 v[158:159], v[146:147], off offset:32 nt
	global_load_dwordx2 v[202:203], v[2:3], off offset:256 nt
	s_and_b64 vcc, exec, s[14:15]
	s_cbranch_vccz .LBB0_922
.LBB0_925:
	global_load_dwordx2 v[200:201], v[2:3], off offset:288 nt
	s_and_b64 vcc, exec, s[14:15]
	s_cbranch_vccnz .LBB0_927
.LBB0_926:
	v_add_co_u32_e32 v2, vcc, 0x1000, v2
	s_nop 1
	v_addc_co_u32_e32 v3, vcc, 0, v3, vcc
	global_load_dwordx2 v[154:155], v[2:3], off offset:288 nt
.LBB0_927:
	v_add_u32_e32 v0, 48, v144
	v_mad_i64_i32 v[220:221], s[30:31], v0, s71, v[190:191]
	global_load_dwordx2 v[198:199], v[220:221], off nt
	s_and_b64 vcc, exec, s[14:15]
	s_cbranch_vccnz .LBB0_931
	v_add_co_u32_e32 v2, vcc, 0x1000, v220
	s_nop 1
	v_addc_co_u32_e32 v3, vcc, 0, v221, vcc
	global_load_dwordx2 v[152:153], v[2:3], off nt
	global_load_dwordx2 v[196:197], v[220:221], off offset:32 nt
	s_and_b64 vcc, exec, s[14:15]
	s_cbranch_vccz .LBB0_932
.LBB0_929:
	global_load_dwordx2 v[194:195], v[220:221], off offset:256 nt
	s_and_b64 vcc, exec, s[14:15]
	s_cbranch_vccnz .LBB0_933
.LBB0_930:
	v_add_co_u32_e32 v2, vcc, 0x1000, v220
	s_nop 1
	v_addc_co_u32_e32 v3, vcc, 0, v221, vcc
	global_load_dwordx2 v[146:147], v[2:3], off offset:256 nt
	global_load_dwordx2 v[192:193], v[220:221], off offset:288 nt
	s_and_b64 vcc, exec, s[14:15]
	s_cbranch_vccz .LBB0_934
	s_branch .LBB0_935
.LBB0_931:
	global_load_dwordx2 v[196:197], v[220:221], off offset:32 nt
	s_and_b64 vcc, exec, s[14:15]
	s_cbranch_vccnz .LBB0_929
.LBB0_932:
	v_add_co_u32_e32 v2, vcc, 0x1000, v220
	s_nop 1
	v_addc_co_u32_e32 v3, vcc, 0, v221, vcc
	global_load_dwordx2 v[150:151], v[2:3], off offset:32 nt
	global_load_dwordx2 v[194:195], v[220:221], off offset:256 nt
	s_and_b64 vcc, exec, s[14:15]
	s_cbranch_vccz .LBB0_930
.LBB0_933:
	global_load_dwordx2 v[192:193], v[220:221], off offset:288 nt
	s_and_b64 vcc, exec, s[14:15]
	s_cbranch_vccnz .LBB0_935
.LBB0_934:
	v_add_co_u32_e32 v2, vcc, 0x1000, v220
	s_nop 1
	v_addc_co_u32_e32 v3, vcc, 0, v221, vcc
	global_load_dwordx2 v[2:3], v[2:3], off offset:288 nt

; __device__ __forceinline__ unsigned cvt_pk_bf16(float lo, float hi) { unsigned r; asm volatile("v_cvt_pk_bf16_f32 %0, %1, %2" : "=v"(r) : "v"(lo), "v"(hi)); return r; }
;     __device__ __forceinline__ void operator()(const f32x4 (&acc)[2][2][4][2], const Unit& u, int wr, int wc, int fr, int fq) const {
;     ...
;         for (int ai = 0; ai < 2; ++ai)
; #pragma unroll
;             for (int m = 0; m < 4; ++m) { const int row = u.pm * BM + ai * HALF + wr * 64 + m * 16 + fr; const int b = row >= 4224 ? 1 : 0, t = row - b * 4224; float ss = 0.f;
; #pragma unroll
;                 for (int bj = 0; bj < 2; ++bj)
; #pragma unroll
;                     for (int n = 0; n < 2; ++n) { const int col = u.pn * BM + bj * HALF + wc * 32 + n * 16 + 4 * fq; float* p = H + (size_t)row * 2048 + col;
;                         const f32x4 v = *(const f32x4*)p + acc[ai][bj][m][n] * s; *(f32x4*)p = v;
;                         if (SSQ != nullptr) { typedef unsigned u32x2 __attribute__((ext_vector_type(2))); u32x2 w; w.x = cvt_pk_bf16(v[0], v[1]); w.y = cvt_pk_bf16(v[2], v[3]); *(u32x2*)(HB + (size_t)row * 2048 + col) = w;
;                             ss += (v[0] * v[0] + v[1] * v[1]) + (v[2] * v[2] + v[3] * v[3]); }
;                         if (OUT != 0ull && t >= 128) *(__attribute__((address_space(1))) f32x4*)(OUT + ((size_t)(b * 4096 + t - 128) * 2048 + col) * 4) = v; }
;                 if (SSQ != nullptr) {
;                     { float p0 = ss, p1 = ss; asm("s_nop 1\n\tv_permlane16_swap_b32 %0, %1" : "+v"(p0), "+v"(p1)); ss = p0 + p1; p0 = ss; p1 = ss; asm("s_nop 1\n\tv_permlane32_swap_b32 %0, %1" : "+v"(p0), "+v"(p1)); ss = p0 + p1; }
;                     if (fq == 0) SSQ[(size_t)row * 32 + 4 * u.pn + wc] = ss; }
;                 asm volatile("" ::: "memory"); }
.LBB0_1355:
	s_add_i32 s0, s0, s39
	v_add_u32_e32 v138, s0, v136
	s_lshl_b32 s0, s44, 8
	s_or_b32 s0, s0, s40
	v_lshl_add_u32 v136, v140, 2, s0
	v_cmp_eq_u32_e32 vcc, 0, v140
	v_lshlrev_b32_e32 v164, 13, v138
	v_lshl_add_u32 v164, v136, 2, v164
	s_lshl_b32 s26, s44, 4
	s_lshl_b32 s0, s38, 2
	s_add_i32 s26, s26, s0
	v_lshl_add_u32 v165, v138, 7, s26
	global_load_dwordx4 v[182:185], v164, s[12:13] nt
	global_load_dwordx4 v[186:189], v164, s[12:13] offset:64 nt
	global_load_dwordx4 v[190:193], v164, s[12:13] offset:512 nt
	global_load_dwordx4 v[194:197], v164, s[12:13] offset:576 nt
	v_add_u32_e32 v242, 0x20000, v164
	global_load_dwordx4 v[198:201], v242, s[12:13] nt
	global_load_dwordx4 v[202:205], v242, s[12:13] offset:64 nt
	global_load_dwordx4 v[206:209], v242, s[12:13] offset:512 nt
	global_load_dwordx4 v[210:213], v242, s[12:13] offset:576 nt
	v_add_u32_e32 v242, 0x40000, v164
	global_load_dwordx4 v[214:217], v242, s[12:13] nt
	global_load_dwordx4 v[218:221], v242, s[12:13] offset:64 nt
	global_load_dwordx4 v[222:225], v242, s[12:13] offset:512 nt
	global_load_dwordx4 v[226:229], v242, s[12:13] offset:576 nt
	v_add_u32_e32 v242, 0x60000, v164
	global_load_dwordx4 v[148:151], v242, s[12:13] nt
	global_load_dwordx4 v[152:155], v242, s[12:13] offset:64 nt
	global_load_dwordx4 v[156:159], v242, s[12:13] offset:512 nt
	global_load_dwordx4 v[160:163], v242, s[12:13] offset:576 nt
	v_mov_b32_e32 v166, v164
	v_lshrrev_b32_e32 v167, 1, v166
	s_waitcnt vmcnt(12)
	v_pk_add_f32 v[128:129], v[128:129], v[184:185]
	v_pk_add_f32 v[126:127], v[126:127], v[182:183]
	global_store_dwordx4 v166, v[126:129], s[12:13]
	v_cvt_pk_bf16_f32 v142, v126, v127
	v_cvt_pk_bf16_f32 v143, v128, v129
	global_store_dwordx2 v167, v[142:143], s[14:15]
	v_mul_f32_e32 v168, v127, v127
	v_mul_f32_e32 v241, v129, v129
	v_fmac_f32_e32 v168, v126, v126
	v_fmac_f32_e32 v241, v128, v128
	v_add_f32_e32 v168, v168, v241
	v_pk_add_f32 v[124:125], v[124:125], v[188:189]
	v_pk_add_f32 v[122:123], v[122:123], v[186:187]
	global_store_dwordx4 v166, v[122:125], s[12:13] offset:64
	v_cvt_pk_bf16_f32 v142, v122, v123
	v_cvt_pk_bf16_f32 v143, v124, v125
	global_store_dwordx2 v167, v[142:143], s[14:15] offset:32
	v_mul_f32_e32 v240, v123, v123
	v_mul_f32_e32 v241, v125, v125
	v_fmac_f32_e32 v240, v122, v122
	v_fmac_f32_e32 v241, v124, v124
	v_add_f32_e32 v240, v240, v241
	v_add_f32_e32 v168, v168, v240
	v_pk_add_f32 v[96:97], v[96:97], v[192:193]
	v_pk_add_f32 v[94:95], v[94:95], v[190:191]
	global_store_dwordx4 v166, v[94:97], s[12:13] offset:512
	v_cvt_pk_bf16_f32 v142, v94, v95
	v_cvt_pk_bf16_f32 v143, v96, v97
	global_store_dwordx2 v167, v[142:143], s[14:15] offset:256
	v_mul_f32_e32 v240, v95, v95
	v_mul_f32_e32 v241, v97, v97
	v_fmac_f32_e32 v240, v94, v94
	v_fmac_f32_e32 v241, v96, v96
	v_add_f32_e32 v240, v240, v241
	v_add_f32_e32 v168, v168, v240
	v_pk_add_f32 v[92:93], v[92:93], v[196:197]
	v_pk_add_f32 v[90:91], v[90:91], v[194:195]
	global_store_dwordx4 v166, v[90:93], s[12:13] offset:576
	v_cvt_pk_bf16_f32 v142, v90, v91
	v_cvt_pk_bf16_f32 v143, v92, v93
	global_store_dwordx2 v167, v[142:143], s[14:15] offset:288
	v_mul_f32_e32 v240, v91, v91
	v_mul_f32_e32 v241, v93, v93
	v_fmac_f32_e32 v240, v90, v90
	v_fmac_f32_e32 v241, v92, v92
	v_add_f32_e32 v240, v240, v241
	v_add_f32_e32 v168, v168, v240
	v_add_u32_e32 v242, 0x100000, v164
	global_load_dwordx4 v[182:185], v242, s[12:13] nt
	global_load_dwordx4 v[186:189], v242, s[12:13] offset:64 nt
	global_load_dwordx4 v[190:193], v242, s[12:13] offset:512 nt
	global_load_dwordx4 v[194:197], v242, s[12:13] offset:576 nt
	v_mov_b32_e32 v169, v168
	s_nop 1
	v_permlane16_swap_b32 v168, v169
	s_nop 1
	v_add_f32_e32 v168, v168, v169
	v_mov_b32_e32 v169, v168
	s_nop 1
	v_permlane32_swap_b32 v169, v168
	v_mov_b32_e32 v243, v165
	s_and_saveexec_b64 s[24:25], vcc
	v_add_f32_e32 v244, v169, v168
	global_store_dword v243, v244, s[8:9]
	s_or_b64 exec, exec, s[24:25]
	v_add_u32_e32 v166, 0x20000, v164
	v_lshrrev_b32_e32 v167, 1, v166
	s_waitcnt vmcnt(21)
	v_pk_add_f32 v[120:121], v[120:121], v[200:201]
	v_pk_add_f32 v[118:119], v[118:119], v[198:199]
	global_store_dwordx4 v166, v[118:121], s[12:13]
	v_cvt_pk_bf16_f32 v142, v118, v119
	v_cvt_pk_bf16_f32 v143, v120, v121
	global_store_dwordx2 v167, v[142:143], s[14:15]
	v_mul_f32_e32 v168, v119, v119
	v_mul_f32_e32 v241, v121, v121
	v_fmac_f32_e32 v168, v118, v118
	v_fmac_f32_e32 v241, v120, v120
	v_add_f32_e32 v168, v168, v241
	v_pk_add_f32 v[116:117], v[116:117], v[204:205]
	v_pk_add_f32 v[114:115], v[114:115], v[202:203]
	global_store_dwordx4 v166, v[114:117], s[12:13] offset:64
	v_cvt_pk_bf16_f32 v142, v114, v115
	v_cvt_pk_bf16_f32 v143, v116, v117
	global_store_dwordx2 v167, v[142:143], s[14:15] offset:32
	v_mul_f32_e32 v240, v115, v115
	v_mul_f32_e32 v241, v117, v117
	v_fmac_f32_e32 v240, v114, v114
	v_fmac_f32_e32 v241, v116, v116
	v_add_f32_e32 v240, v240, v241
	v_add_f32_e32 v168, v168, v240
	v_pk_add_f32 v[88:89], v[88:89], v[208:209]
	v_pk_add_f32 v[86:87], v[86:87], v[206:207]
	global_store_dwordx4 v166, v[86:89], s[12:13] offset:512
	v_cvt_pk_bf16_f32 v142, v86, v87
	v_cvt_pk_bf16_f32 v143, v88, v89
	global_store_dwordx2 v167, v[142:143], s[14:15] offset:256
	v_mul_f32_e32 v240, v87, v87
	v_mul_f32_e32 v241, v89, v89
	v_fmac_f32_e32 v240, v86, v86
	v_fmac_f32_e32 v241, v88, v88
	v_add_f32_e32 v240, v240, v241
	v_add_f32_e32 v168, v168, v240
	v_pk_add_f32 v[84:85], v[84:85], v[212:213]
	v_pk_add_f32 v[82:83], v[82:83], v[210:211]
	global_store_dwordx4 v166, v[82:85], s[12:13] offset:576
	v_cvt_pk_bf16_f32 v142, v82, v83
	v_cvt_pk_bf16_f32 v143, v84, v85
	global_store_dwordx2 v167, v[142:143], s[14:15] offset:288
	v_mul_f32_e32 v240, v83, v83
	v_mul_f32_e32 v241, v85, v85
	v_fmac_f32_e32 v240, v82, v82
	v_fmac_f32_e32 v241, v84, v84
	v_add_f32_e32 v240, v240, v241
	v_add_f32_e32 v168, v168, v240
	v_add_u32_e32 v242, 0x120000, v164
	global_load_dwordx4 v[198:201], v242, s[12:13] nt
	global_load_dwordx4 v[202:205], v242, s[12:13] offset:64 nt
	global_load_dwordx4 v[206:209], v242, s[12:13] offset:512 nt
	global_load_dwordx4 v[210:213], v242, s[12:13] offset:576 nt
	v_mov_b32_e32 v169, v168
	s_nop 1
	v_permlane16_swap_b32 v168, v169
	s_nop 1
	v_add_f32_e32 v168, v168, v169
	v_mov_b32_e32 v169, v168
	s_nop 1
	v_permlane32_swap_b32 v169, v168
	v_add_u32_e32 v243, 0x800, v165
	s_and_saveexec_b64 s[24:25], vcc
	v_add_f32_e32 v244, v169, v168
	global_store_dword v243, v244, s[8:9]
	s_or_b64 exec, exec, s[24:25]
	v_add_u32_e32 v166, 0x40000, v164
	v_lshrrev_b32_e32 v167, 1, v166
	s_waitcnt vmcnt(30)
; __device__ __forceinline__ unsigned cvt_pk_bf16(float lo, float hi) { unsigned r; asm volatile("v_cvt_pk_bf16_f32 %0, %1, %2" : "=v"(r) : "v"(lo), "v"(hi)); return r; }
;     __device__ __forceinline__ void operator()(const f32x4 (&acc)[2][2][4][2], const Unit& u, int wr, int wc, int fr, int fq) const {
;     ...
;         for (int ai = 0; ai < 2; ++ai)
; #pragma unroll
;             for (int m = 0; m < 4; ++m) { const int row = u.pm * BM + ai * HALF + wr * 64 + m * 16 + fr; const int b = row >= 4224 ? 1 : 0, t = row - b * 4224; float ss = 0.f;
; #pragma unroll
;                 for (int bj = 0; bj < 2; ++bj)
; #pragma unroll
;                     for (int n = 0; n < 2; ++n) { const int col = u.pn * BM + bj * HALF + wc * 32 + n * 16 + 4 * fq; float* p = H + (size_t)row * 2048 + col;
;                         const f32x4 v = *(const f32x4*)p + acc[ai][bj][m][n] * s; *(f32x4*)p = v;
;                         if (SSQ != nullptr) { typedef unsigned u32x2 __attribute__((ext_vector_type(2))); u32x2 w; w.x = cvt_pk_bf16(v[0], v[1]); w.y = cvt_pk_bf16(v[2], v[3]); *(u32x2*)(HB + (size_t)row * 2048 + col) = w;
;                             ss += (v[0] * v[0] + v[1] * v[1]) + (v[2] * v[2] + v[3] * v[3]); }
;                         if (OUT != 0ull && t >= 128) *(__attribute__((address_space(1))) f32x4*)(OUT + ((size_t)(b * 4096 + t - 128) * 2048 + col) * 4) = v; }
;                 if (SSQ != nullptr) {
;                     { float p0 = ss, p1 = ss; asm("s_nop 1\n\tv_permlane16_swap_b32 %0, %1" : "+v"(p0), "+v"(p1)); ss = p0 + p1; p0 = ss; p1 = ss; asm("s_nop 1\n\tv_permlane32_swap_b32 %0, %1" : "+v"(p0), "+v"(p1)); ss = p0 + p1; }
;                     if (fq == 0) SSQ[(size_t)row * 32 + 4 * u.pn + wc] = ss; }
;                 asm volatile("" ::: "memory"); }
	v_pk_add_f32 v[112:113], v[112:113], v[216:217]
	v_pk_add_f32 v[110:111], v[110:111], v[214:215]
	global_store_dwordx4 v166, v[110:113], s[12:13]
	v_cvt_pk_bf16_f32 v142, v110, v111
	v_cvt_pk_bf16_f32 v143, v112, v113
	global_store_dwordx2 v167, v[142:143], s[14:15]
	v_mul_f32_e32 v168, v111, v111
	v_mul_f32_e32 v241, v113, v113
	v_fmac_f32_e32 v168, v110, v110
	v_fmac_f32_e32 v241, v112, v112
	v_add_f32_e32 v168, v168, v241
	v_pk_add_f32 v[108:109], v[108:109], v[220:221]
	v_pk_add_f32 v[106:107], v[106:107], v[218:219]
	global_store_dwordx4 v166, v[106:109], s[12:13] offset:64
	v_cvt_pk_bf16_f32 v142, v106, v107
	v_cvt_pk_bf16_f32 v143, v108, v109
	global_store_dwordx2 v167, v[142:143], s[14:15] offset:32
	v_mul_f32_e32 v240, v107, v107
	v_mul_f32_e32 v241, v109, v109
	v_fmac_f32_e32 v240, v106, v106
	v_fmac_f32_e32 v241, v108, v108
	v_add_f32_e32 v240, v240, v241
	v_add_f32_e32 v168, v168, v240
	v_pk_add_f32 v[80:81], v[80:81], v[224:225]
	v_pk_add_f32 v[78:79], v[78:79], v[222:223]
	global_store_dwordx4 v166, v[78:81], s[12:13] offset:512
	v_cvt_pk_bf16_f32 v142, v78, v79
	v_cvt_pk_bf16_f32 v143, v80, v81
	global_store_dwordx2 v167, v[142:143], s[14:15] offset:256
	v_mul_f32_e32 v240, v79, v79
	v_mul_f32_e32 v241, v81, v81
	v_fmac_f32_e32 v240, v78, v78
	v_fmac_f32_e32 v241, v80, v80
	v_add_f32_e32 v240, v240, v241
	v_add_f32_e32 v168, v168, v240
	v_pk_add_f32 v[76:77], v[76:77], v[228:229]
	v_pk_add_f32 v[74:75], v[74:75], v[226:227]
	global_store_dwordx4 v166, v[74:77], s[12:13] offset:576
	v_cvt_pk_bf16_f32 v142, v74, v75
	v_cvt_pk_bf16_f32 v143, v76, v77
	global_store_dwordx2 v167, v[142:143], s[14:15] offset:288
	v_mul_f32_e32 v240, v75, v75
	v_mul_f32_e32 v241, v77, v77
	v_fmac_f32_e32 v240, v74, v74
	v_fmac_f32_e32 v241, v76, v76
	v_add_f32_e32 v240, v240, v241
	v_add_f32_e32 v168, v168, v240
	v_add_u32_e32 v242, 0x140000, v164
	global_load_dwordx4 v[214:217], v242, s[12:13] nt
	global_load_dwordx4 v[218:221], v242, s[12:13] offset:64 nt
	global_load_dwordx4 v[222:225], v242, s[12:13] offset:512 nt
	global_load_dwordx4 v[226:229], v242, s[12:13] offset:576 nt
	v_mov_b32_e32 v169, v168
	s_nop 1
	v_permlane16_swap_b32 v168, v169
	s_nop 1
	v_add_f32_e32 v168, v168, v169
	v_mov_b32_e32 v169, v168
	s_nop 1
	v_permlane32_swap_b32 v169, v168
	v_add_u32_e32 v243, 0x1000, v165
	s_and_saveexec_b64 s[24:25], vcc
	v_add_f32_e32 v244, v169, v168
	global_store_dword v243, v244, s[8:9]
	s_or_b64 exec, exec, s[24:25]
	v_add_u32_e32 v166, 0x60000, v164
	v_lshrrev_b32_e32 v167, 1, v166
	s_waitcnt vmcnt(39)
	v_pk_add_f32 v[104:105], v[104:105], v[150:151]
	v_pk_add_f32 v[102:103], v[102:103], v[148:149]
	global_store_dwordx4 v166, v[102:105], s[12:13]
	v_cvt_pk_bf16_f32 v142, v102, v103
	v_cvt_pk_bf16_f32 v143, v104, v105
	global_store_dwordx2 v167, v[142:143], s[14:15]
	v_mul_f32_e32 v168, v103, v103
	v_mul_f32_e32 v241, v105, v105
	v_fmac_f32_e32 v168, v102, v102
	v_fmac_f32_e32 v241, v104, v104
	v_add_f32_e32 v168, v168, v241
	v_pk_add_f32 v[100:101], v[100:101], v[154:155]
	v_pk_add_f32 v[98:99], v[98:99], v[152:153]
	global_store_dwordx4 v166, v[98:101], s[12:13] offset:64
	v_cvt_pk_bf16_f32 v142, v98, v99
	v_cvt_pk_bf16_f32 v143, v100, v101
	global_store_dwordx2 v167, v[142:143], s[14:15] offset:32
	v_mul_f32_e32 v240, v99, v99
	v_mul_f32_e32 v241, v101, v101
	v_fmac_f32_e32 v240, v98, v98
	v_fmac_f32_e32 v241, v100, v100
	v_add_f32_e32 v240, v240, v241
	v_add_f32_e32 v168, v168, v240
	v_pk_add_f32 v[72:73], v[72:73], v[158:159]
	v_pk_add_f32 v[70:71], v[70:71], v[156:157]
	global_store_dwordx4 v166, v[70:73], s[12:13] offset:512
	v_cvt_pk_bf16_f32 v142, v70, v71
	v_cvt_pk_bf16_f32 v143, v72, v73
	global_store_dwordx2 v167, v[142:143], s[14:15] offset:256
	v_mul_f32_e32 v240, v71, v71
	v_mul_f32_e32 v241, v73, v73
	v_fmac_f32_e32 v240, v70, v70
	v_fmac_f32_e32 v241, v72, v72
	v_add_f32_e32 v240, v240, v241
	v_add_f32_e32 v168, v168, v240
	v_pk_add_f32 v[68:69], v[68:69], v[162:163]
	v_pk_add_f32 v[66:67], v[66:67], v[160:161]
	global_store_dwordx4 v166, v[66:69], s[12:13] offset:576
	v_cvt_pk_bf16_f32 v142, v66, v67
	v_cvt_pk_bf16_f32 v143, v68, v69
	global_store_dwordx2 v167, v[142:143], s[14:15] offset:288
	v_mul_f32_e32 v240, v67, v67
	v_mul_f32_e32 v241, v69, v69
	v_fmac_f32_e32 v240, v66, v66
	v_fmac_f32_e32 v241, v68, v68
	v_add_f32_e32 v240, v240, v241
	v_add_f32_e32 v168, v168, v240
	v_add_u32_e32 v242, 0x160000, v164
	global_load_dwordx4 v[148:151], v242, s[12:13] nt
	global_load_dwordx4 v[152:155], v242, s[12:13] offset:64 nt
	global_load_dwordx4 v[156:159], v242, s[12:13] offset:512 nt
	global_load_dwordx4 v[160:163], v242, s[12:13] offset:576 nt
	v_mov_b32_e32 v169, v168
	s_nop 1
	v_permlane16_swap_b32 v168, v169
	s_nop 1
	v_add_f32_e32 v168, v168, v169
	v_mov_b32_e32 v169, v168
	s_nop 1
	v_permlane32_swap_b32 v169, v168
	v_add_u32_e32 v243, 0x1800, v165
	s_and_saveexec_b64 s[24:25], vcc
	v_add_f32_e32 v244, v169, v168
	global_store_dword v243, v244, s[8:9]
	s_or_b64 exec, exec, s[24:25]
	v_add_u32_e32 v166, 0x100000, v164
	v_lshrrev_b32_e32 v167, 1, v166
	s_waitcnt vmcnt(40)
; __device__ __forceinline__ unsigned cvt_pk_bf16(float lo, float hi) { unsigned r; asm volatile("v_cvt_pk_bf16_f32 %0, %1, %2" : "=v"(r) : "v"(lo), "v"(hi)); return r; }
;     __device__ __forceinline__ void operator()(const f32x4 (&acc)[2][2][4][2], const Unit& u, int wr, int wc, int fr, int fq) const {
;     ...
;         for (int ai = 0; ai < 2; ++ai)
; #pragma unroll
;             for (int m = 0; m < 4; ++m) { const int row = u.pm * BM + ai * HALF + wr * 64 + m * 16 + fr; const int b = row >= 4224 ? 1 : 0, t = row - b * 4224; float ss = 0.f;
; #pragma unroll
;                 for (int bj = 0; bj < 2; ++bj)
; #pragma unroll
;                     for (int n = 0; n < 2; ++n) { const int col = u.pn * BM + bj * HALF + wc * 32 + n * 16 + 4 * fq; float* p = H + (size_t)row * 2048 + col;
;                         const f32x4 v = *(const f32x4*)p + acc[ai][bj][m][n] * s; *(f32x4*)p = v;
;                         if (SSQ != nullptr) { typedef unsigned u32x2 __attribute__((ext_vector_type(2))); u32x2 w; w.x = cvt_pk_bf16(v[0], v[1]); w.y = cvt_pk_bf16(v[2], v[3]); *(u32x2*)(HB + (size_t)row * 2048 + col) = w;
;                             ss += (v[0] * v[0] + v[1] * v[1]) + (v[2] * v[2] + v[3] * v[3]); }
;                         if (OUT != 0ull && t >= 128) *(__attribute__((address_space(1))) f32x4*)(OUT + ((size_t)(b * 4096 + t - 128) * 2048 + col) * 4) = v; }
;                 if (SSQ != nullptr) {
;                     { float p0 = ss, p1 = ss; asm("s_nop 1\n\tv_permlane16_swap_b32 %0, %1" : "+v"(p0), "+v"(p1)); ss = p0 + p1; p0 = ss; p1 = ss; asm("s_nop 1\n\tv_permlane32_swap_b32 %0, %1" : "+v"(p0), "+v"(p1)); ss = p0 + p1; }
;                     if (fq == 0) SSQ[(size_t)row * 32 + 4 * u.pn + wc] = ss; }
;                 asm volatile("" ::: "memory"); }
	v_pk_add_f32 v[64:65], v[64:65], v[184:185]
	v_pk_add_f32 v[62:63], v[62:63], v[182:183]
	global_store_dwordx4 v166, v[62:65], s[12:13]
	v_cvt_pk_bf16_f32 v142, v62, v63
	v_cvt_pk_bf16_f32 v143, v64, v65
	global_store_dwordx2 v167, v[142:143], s[14:15]
	v_mul_f32_e32 v168, v63, v63
	v_mul_f32_e32 v241, v65, v65
	v_fmac_f32_e32 v168, v62, v62
	v_fmac_f32_e32 v241, v64, v64
	v_add_f32_e32 v168, v168, v241
	v_pk_add_f32 v[60:61], v[60:61], v[188:189]
	v_pk_add_f32 v[58:59], v[58:59], v[186:187]
	global_store_dwordx4 v166, v[58:61], s[12:13] offset:64
	v_cvt_pk_bf16_f32 v142, v58, v59
	v_cvt_pk_bf16_f32 v143, v60, v61
	global_store_dwordx2 v167, v[142:143], s[14:15] offset:32
	v_mul_f32_e32 v240, v59, v59
	v_mul_f32_e32 v241, v61, v61
	v_fmac_f32_e32 v240, v58, v58
	v_fmac_f32_e32 v241, v60, v60
	v_add_f32_e32 v240, v240, v241
	v_add_f32_e32 v168, v168, v240
	v_pk_add_f32 v[32:33], v[32:33], v[192:193]
	v_pk_add_f32 v[30:31], v[30:31], v[190:191]
	global_store_dwordx4 v166, v[30:33], s[12:13] offset:512
	v_cvt_pk_bf16_f32 v142, v30, v31
	v_cvt_pk_bf16_f32 v143, v32, v33
	global_store_dwordx2 v167, v[142:143], s[14:15] offset:256
	v_mul_f32_e32 v240, v31, v31
	v_mul_f32_e32 v241, v33, v33
	v_fmac_f32_e32 v240, v30, v30
	v_fmac_f32_e32 v241, v32, v32
	v_add_f32_e32 v240, v240, v241
	v_add_f32_e32 v168, v168, v240
	v_pk_add_f32 v[28:29], v[28:29], v[196:197]
	v_pk_add_f32 v[26:27], v[26:27], v[194:195]
	global_store_dwordx4 v166, v[26:29], s[12:13] offset:576
	v_cvt_pk_bf16_f32 v142, v26, v27
	v_cvt_pk_bf16_f32 v143, v28, v29
	global_store_dwordx2 v167, v[142:143], s[14:15] offset:288
	v_mul_f32_e32 v240, v27, v27
	v_mul_f32_e32 v241, v29, v29
	v_fmac_f32_e32 v240, v26, v26
	v_fmac_f32_e32 v241, v28, v28
	v_add_f32_e32 v240, v240, v241
	v_add_f32_e32 v168, v168, v240
	v_mov_b32_e32 v169, v168
	s_nop 1
	v_permlane16_swap_b32 v168, v169
	s_nop 1
	v_add_f32_e32 v168, v168, v169
	v_mov_b32_e32 v169, v168
	s_nop 1
	v_permlane32_swap_b32 v169, v168
	v_add_u32_e32 v243, 0x4000, v165
	s_and_saveexec_b64 s[24:25], vcc
	v_add_f32_e32 v244, v169, v168
	global_store_dword v243, v244, s[8:9]
	s_or_b64 exec, exec, s[24:25]
	v_add_u32_e32 v166, 0x120000, v164
	v_lshrrev_b32_e32 v167, 1, v166
	s_waitcnt vmcnt(36)
	v_pk_add_f32 v[56:57], v[56:57], v[200:201]
	v_pk_add_f32 v[54:55], v[54:55], v[198:199]
	global_store_dwordx4 v166, v[54:57], s[12:13]
	v_cvt_pk_bf16_f32 v142, v54, v55
	v_cvt_pk_bf16_f32 v143, v56, v57
	global_store_dwordx2 v167, v[142:143], s[14:15]
	v_mul_f32_e32 v168, v55, v55
	v_mul_f32_e32 v241, v57, v57
	v_fmac_f32_e32 v168, v54, v54
	v_fmac_f32_e32 v241, v56, v56
	v_add_f32_e32 v168, v168, v241
	v_pk_add_f32 v[52:53], v[52:53], v[204:205]
	v_pk_add_f32 v[50:51], v[50:51], v[202:203]
	global_store_dwordx4 v166, v[50:53], s[12:13] offset:64
	v_cvt_pk_bf16_f32 v142, v50, v51
	v_cvt_pk_bf16_f32 v143, v52, v53
	global_store_dwordx2 v167, v[142:143], s[14:15] offset:32
	v_mul_f32_e32 v240, v51, v51
	v_mul_f32_e32 v241, v53, v53
	v_fmac_f32_e32 v240, v50, v50
	v_fmac_f32_e32 v241, v52, v52
	v_add_f32_e32 v240, v240, v241
	v_add_f32_e32 v168, v168, v240
	v_pk_add_f32 v[24:25], v[24:25], v[208:209]
	v_pk_add_f32 v[22:23], v[22:23], v[206:207]
	global_store_dwordx4 v166, v[22:25], s[12:13] offset:512
	v_cvt_pk_bf16_f32 v142, v22, v23
	v_cvt_pk_bf16_f32 v143, v24, v25
	global_store_dwordx2 v167, v[142:143], s[14:15] offset:256
	v_mul_f32_e32 v240, v23, v23
	v_mul_f32_e32 v241, v25, v25
	v_fmac_f32_e32 v240, v22, v22
	v_fmac_f32_e32 v241, v24, v24
	v_add_f32_e32 v240, v240, v241
	v_add_f32_e32 v168, v168, v240
	v_pk_add_f32 v[20:21], v[20:21], v[212:213]
	v_pk_add_f32 v[18:19], v[18:19], v[210:211]
	global_store_dwordx4 v166, v[18:21], s[12:13] offset:576
	v_cvt_pk_bf16_f32 v142, v18, v19
	v_cvt_pk_bf16_f32 v143, v20, v21
	global_store_dwordx2 v167, v[142:143], s[14:15] offset:288
	v_mul_f32_e32 v240, v19, v19
	v_mul_f32_e32 v241, v21, v21
	v_fmac_f32_e32 v240, v18, v18
	v_fmac_f32_e32 v241, v20, v20
	v_add_f32_e32 v240, v240, v241
	v_add_f32_e32 v168, v168, v240
	v_mov_b32_e32 v169, v168
	s_nop 1
	v_permlane16_swap_b32 v168, v169
	s_nop 1
	v_add_f32_e32 v168, v168, v169
	v_mov_b32_e32 v169, v168
	s_nop 1
	v_permlane32_swap_b32 v169, v168
	v_add_u32_e32 v243, 0x4800, v165
	s_and_saveexec_b64 s[24:25], vcc
	v_add_f32_e32 v244, v169, v168
	global_store_dword v243, v244, s[8:9]
	s_or_b64 exec, exec, s[24:25]
	v_add_u32_e32 v166, 0x140000, v164
	v_lshrrev_b32_e32 v167, 1, v166
	s_waitcnt vmcnt(32)
; __device__ __forceinline__ unsigned cvt_pk_bf16(float lo, float hi) { unsigned r; asm volatile("v_cvt_pk_bf16_f32 %0, %1, %2" : "=v"(r) : "v"(lo), "v"(hi)); return r; }
;     __device__ __forceinline__ void operator()(const f32x4 (&acc)[2][2][4][2], const Unit& u, int wr, int wc, int fr, int fq) const {
;     ...
;         for (int ai = 0; ai < 2; ++ai)
; #pragma unroll
;             for (int m = 0; m < 4; ++m) { const int row = u.pm * BM + ai * HALF + wr * 64 + m * 16 + fr; const int b = row >= 4224 ? 1 : 0, t = row - b * 4224; float ss = 0.f;
; #pragma unroll
;                 for (int bj = 0; bj < 2; ++bj)
; #pragma unroll
;                     for (int n = 0; n < 2; ++n) { const int col = u.pn * BM + bj * HALF + wc * 32 + n * 16 + 4 * fq; float* p = H + (size_t)row * 2048 + col;
;                         const f32x4 v = *(const f32x4*)p + acc[ai][bj][m][n] * s; *(f32x4*)p = v;
;                         if (SSQ != nullptr) { typedef unsigned u32x2 __attribute__((ext_vector_type(2))); u32x2 w; w.x = cvt_pk_bf16(v[0], v[1]); w.y = cvt_pk_bf16(v[2], v[3]); *(u32x2*)(HB + (size_t)row * 2048 + col) = w;
;                             ss += (v[0] * v[0] + v[1] * v[1]) + (v[2] * v[2] + v[3] * v[3]); }
;                         if (OUT != 0ull && t >= 128) *(__attribute__((address_space(1))) f32x4*)(OUT + ((size_t)(b * 4096 + t - 128) * 2048 + col) * 4) = v; }
;                 if (SSQ != nullptr) {
;                     { float p0 = ss, p1 = ss; asm("s_nop 1\n\tv_permlane16_swap_b32 %0, %1" : "+v"(p0), "+v"(p1)); ss = p0 + p1; p0 = ss; p1 = ss; asm("s_nop 1\n\tv_permlane32_swap_b32 %0, %1" : "+v"(p0), "+v"(p1)); ss = p0 + p1; }
;                     if (fq == 0) SSQ[(size_t)row * 32 + 4 * u.pn + wc] = ss; }
;                 asm volatile("" ::: "memory"); }
	v_pk_add_f32 v[48:49], v[48:49], v[216:217]
	v_pk_add_f32 v[46:47], v[46:47], v[214:215]
	global_store_dwordx4 v166, v[46:49], s[12:13]
	v_cvt_pk_bf16_f32 v142, v46, v47
	v_cvt_pk_bf16_f32 v143, v48, v49
	global_store_dwordx2 v167, v[142:143], s[14:15]
	v_mul_f32_e32 v168, v47, v47
	v_mul_f32_e32 v241, v49, v49
	v_fmac_f32_e32 v168, v46, v46
	v_fmac_f32_e32 v241, v48, v48
	v_add_f32_e32 v168, v168, v241
	v_pk_add_f32 v[44:45], v[44:45], v[220:221]
	v_pk_add_f32 v[42:43], v[42:43], v[218:219]
	global_store_dwordx4 v166, v[42:45], s[12:13] offset:64
	v_cvt_pk_bf16_f32 v142, v42, v43
	v_cvt_pk_bf16_f32 v143, v44, v45
	global_store_dwordx2 v167, v[142:143], s[14:15] offset:32
	v_mul_f32_e32 v240, v43, v43
	v_mul_f32_e32 v241, v45, v45
	v_fmac_f32_e32 v240, v42, v42
	v_fmac_f32_e32 v241, v44, v44
	v_add_f32_e32 v240, v240, v241
	v_add_f32_e32 v168, v168, v240
	v_pk_add_f32 v[16:17], v[16:17], v[224:225]
	v_pk_add_f32 v[14:15], v[14:15], v[222:223]
	global_store_dwordx4 v166, v[14:17], s[12:13] offset:512
	v_cvt_pk_bf16_f32 v142, v14, v15
	v_cvt_pk_bf16_f32 v143, v16, v17
	global_store_dwordx2 v167, v[142:143], s[14:15] offset:256
	v_mul_f32_e32 v240, v15, v15
	v_mul_f32_e32 v241, v17, v17
	v_fmac_f32_e32 v240, v14, v14
	v_fmac_f32_e32 v241, v16, v16
	v_add_f32_e32 v240, v240, v241
	v_add_f32_e32 v168, v168, v240
	v_pk_add_f32 v[12:13], v[12:13], v[228:229]
	v_pk_add_f32 v[10:11], v[10:11], v[226:227]
	global_store_dwordx4 v166, v[10:13], s[12:13] offset:576
	v_cvt_pk_bf16_f32 v142, v10, v11
	v_cvt_pk_bf16_f32 v143, v12, v13
	global_store_dwordx2 v167, v[142:143], s[14:15] offset:288
	v_mul_f32_e32 v240, v11, v11
	v_mul_f32_e32 v241, v13, v13
	v_fmac_f32_e32 v240, v10, v10
	v_fmac_f32_e32 v241, v12, v12
	v_add_f32_e32 v240, v240, v241
	v_add_f32_e32 v168, v168, v240
	v_mov_b32_e32 v169, v168
	s_nop 1
	v_permlane16_swap_b32 v168, v169
	s_nop 1
	v_add_f32_e32 v168, v168, v169
	v_mov_b32_e32 v169, v168
	s_nop 1
	v_permlane32_swap_b32 v169, v168
	v_add_u32_e32 v243, 0x5000, v165
	s_and_saveexec_b64 s[24:25], vcc
	v_add_f32_e32 v244, v169, v168
	global_store_dword v243, v244, s[8:9]
	s_or_b64 exec, exec, s[24:25]
	v_add_u32_e32 v166, 0x160000, v164
	v_lshrrev_b32_e32 v167, 1, v166
	s_waitcnt vmcnt(28)
	v_pk_add_f32 v[40:41], v[40:41], v[150:151]
	v_pk_add_f32 v[38:39], v[38:39], v[148:149]
	global_store_dwordx4 v166, v[38:41], s[12:13]
	v_cvt_pk_bf16_f32 v142, v38, v39
	v_cvt_pk_bf16_f32 v143, v40, v41
	global_store_dwordx2 v167, v[142:143], s[14:15]
	v_mul_f32_e32 v168, v39, v39
	v_mul_f32_e32 v241, v41, v41
	v_fmac_f32_e32 v168, v38, v38
	v_fmac_f32_e32 v241, v40, v40
	v_add_f32_e32 v168, v168, v241
	v_pk_add_f32 v[36:37], v[36:37], v[154:155]
	v_pk_add_f32 v[34:35], v[34:35], v[152:153]
	global_store_dwordx4 v166, v[34:37], s[12:13] offset:64
	v_cvt_pk_bf16_f32 v142, v34, v35
	v_cvt_pk_bf16_f32 v143, v36, v37
	global_store_dwordx2 v167, v[142:143], s[14:15] offset:32
	v_mul_f32_e32 v240, v35, v35
	v_mul_f32_e32 v241, v37, v37
	v_fmac_f32_e32 v240, v34, v34
	v_fmac_f32_e32 v241, v36, v36
	v_add_f32_e32 v240, v240, v241
	v_add_f32_e32 v168, v168, v240
	v_pk_add_f32 v[8:9], v[8:9], v[158:159]
	v_pk_add_f32 v[6:7], v[6:7], v[156:157]
	global_store_dwordx4 v166, v[6:9], s[12:13] offset:512
	v_cvt_pk_bf16_f32 v142, v6, v7
	v_cvt_pk_bf16_f32 v143, v8, v9
	global_store_dwordx2 v167, v[142:143], s[14:15] offset:256
	v_mul_f32_e32 v240, v7, v7
	v_mul_f32_e32 v241, v9, v9
	v_fmac_f32_e32 v240, v6, v6
	v_fmac_f32_e32 v241, v8, v8
	v_add_f32_e32 v240, v240, v241
	v_add_f32_e32 v168, v168, v240
	v_pk_add_f32 v[4:5], v[4:5], v[162:163]
	v_pk_add_f32 v[2:3], v[2:3], v[160:161]
	global_store_dwordx4 v166, v[2:5], s[12:13] offset:576
	v_cvt_pk_bf16_f32 v142, v2, v3
	v_cvt_pk_bf16_f32 v143, v4, v5
	global_store_dwordx2 v167, v[142:143], s[14:15] offset:288
	v_mul_f32_e32 v240, v3, v3
	v_mul_f32_e32 v241, v5, v5
	v_fmac_f32_e32 v240, v2, v2
	v_fmac_f32_e32 v241, v4, v4
	v_add_f32_e32 v240, v240, v241
	v_add_f32_e32 v168, v168, v240
	v_mov_b32_e32 v169, v168
	s_nop 1
	v_permlane16_swap_b32 v168, v169
	s_nop 1
	v_add_f32_e32 v168, v168, v169
	v_mov_b32_e32 v169, v168
	s_nop 1
	v_permlane32_swap_b32 v169, v168
	v_add_u32_e32 v243, 0x5800, v165
	s_and_saveexec_b64 s[24:25], vcc
	v_add_f32_e32 v244, v169, v168
	global_store_dword v243, v244, s[8:9]
	s_or_b64 exec, exec, s[24:25]
	s_andn2_b64 vcc, exec, s[22:23]
	s_mov_b64 s[22:23], -1
	s_cbranch_vccnz .LBB0_1343

; __device__ __forceinline__ unsigned cvt_pk_bf16(float lo, float hi) { unsigned r; asm volatile("v_cvt_pk_bf16_f32 %0, %1, %2" : "=v"(r) : "v"(lo), "v"(hi)); return r; }
;     __device__ __forceinline__ void operator()(const f32x4 (&acc)[2][2][4][2], const Unit& u, int wr, int wc, int fr, int fq) const {
;     ...
;         for (int ai = 0; ai < 2; ++ai)
; #pragma unroll
;             for (int m = 0; m < 4; ++m) { const int row = u.pm * BM + ai * HALF + wr * 64 + m * 16 + fr; const int b = row >= 4224 ? 1 : 0, t = row - b * 4224; float ss = 0.f;
; #pragma unroll
;                 for (int bj = 0; bj < 2; ++bj)
; #pragma unroll
;                     for (int n = 0; n < 2; ++n) { const int col = u.pn * BM + bj * HALF + wc * 32 + n * 16 + 4 * fq; float* p = H + (size_t)row * 2048 + col;
;                         const f32x4 v = *(const f32x4*)p + acc[ai][bj][m][n] * s; *(f32x4*)p = v;
;                         if (SSQ != nullptr) { typedef unsigned u32x2 __attribute__((ext_vector_type(2))); u32x2 w; w.x = cvt_pk_bf16(v[0], v[1]); w.y = cvt_pk_bf16(v[2], v[3]); *(u32x2*)(HB + (size_t)row * 2048 + col) = w;
;                             ss += (v[0] * v[0] + v[1] * v[1]) + (v[2] * v[2] + v[3] * v[3]); }
;                         if (OUT != 0ull && t >= 128) *(__attribute__((address_space(1))) f32x4*)(OUT + ((size_t)(b * 4096 + t - 128) * 2048 + col) * 4) = v; }
;                 if (SSQ != nullptr) {
;                     { float p0 = ss, p1 = ss; asm("s_nop 1\n\tv_permlane16_swap_b32 %0, %1" : "+v"(p0), "+v"(p1)); ss = p0 + p1; p0 = ss; p1 = ss; asm("s_nop 1\n\tv_permlane32_swap_b32 %0, %1" : "+v"(p0), "+v"(p1)); ss = p0 + p1; }
;                     if (fq == 0) SSQ[(size_t)row * 32 + 4 * u.pn + wc] = ss; }
;                 asm volatile("" ::: "memory"); }
.LBB0_1584:
	s_add_i32 s0, s0, s45
	v_add_u32_e32 v144, s0, v0
	s_lshl_b32 s0, s68, 8
	v_ashrrev_i32_e32 v145, 31, v144
	s_or_b32 s0, s0, s48
	v_lshl_add_u32 v142, v158, 2, s0
	s_and_b64 vcc, exec, s[16:17]
	s_cbranch_vccz .Lnepi_slow
	s_and_b64 vcc, exec, s[30:31]
	s_cbranch_vccnz .Lnepi_slow
	v_cmp_eq_u32_e32 vcc, 0, v158
	v_lshlrev_b32_e32 v159, 13, v144
	v_lshl_add_u32 v159, v142, 2, v159
	s_lshl_b32 s36, s68, 4
	s_lshl_b32 s0, s44, 2
	s_add_i32 s36, s36, s0
	v_lshl_add_u32 v160, v144, 7, s36
	global_load_dwordx4 v[182:185], v159, s[14:15] nt
	global_load_dwordx4 v[186:189], v159, s[14:15] offset:64 nt
	global_load_dwordx4 v[190:193], v159, s[14:15] offset:512 nt
	global_load_dwordx4 v[194:197], v159, s[14:15] offset:576 nt
	v_add_u32_e32 v241, 0x20000, v159
	global_load_dwordx4 v[198:201], v241, s[14:15] nt
	global_load_dwordx4 v[202:205], v241, s[14:15] offset:64 nt
	global_load_dwordx4 v[206:209], v241, s[14:15] offset:512 nt
	global_load_dwordx4 v[210:213], v241, s[14:15] offset:576 nt
	v_add_u32_e32 v241, 0x40000, v159
	global_load_dwordx4 v[214:217], v241, s[14:15] nt
	global_load_dwordx4 v[218:221], v241, s[14:15] offset:64 nt
	global_load_dwordx4 v[222:225], v241, s[14:15] offset:512 nt
	global_load_dwordx4 v[226:229], v241, s[14:15] offset:576 nt
	v_add_u32_e32 v241, 0x60000, v159
	global_load_dwordx4 v[146:149], v241, s[14:15] nt
	global_load_dwordx4 v[150:153], v241, s[14:15] offset:64 nt
	global_load_dwordx4 v[154:157], v241, s[14:15] offset:512 nt
	global_load_dwordx4 v[130:133], v241, s[14:15] offset:576 nt
	v_mov_b32_e32 v161, v159
	v_lshrrev_b32_e32 v166, 1, v161
	s_waitcnt vmcnt(12)
	v_pk_fma_f32 v[128:129], v[128:129], 0.5, v[184:185] op_sel_hi:[1,0,1]
	v_pk_fma_f32 v[126:127], v[126:127], 0.5, v[182:183] op_sel_hi:[1,0,1]
	global_store_dwordx4 v161, v[126:129], s[14:15]
	v_cvt_pk_bf16_f32 v244, v126, v127
	v_cvt_pk_bf16_f32 v245, v128, v129
	global_store_dwordx2 v166, v[244:245], s[20:21]
	v_mul_f32_e32 v167, v127, v127
	v_mul_f32_e32 v143, v126, v126
	v_mul_f32_e32 v145, v128, v128
	v_mul_f32_e32 v142, v129, v129
	v_add_f32_e32 v167, v167, v143
	v_add_f32_e32 v240, v145, v142
	v_add_f32_e32 v167, v167, v240
	v_pk_fma_f32 v[124:125], v[124:125], 0.5, v[188:189] op_sel_hi:[1,0,1]
	v_pk_fma_f32 v[122:123], v[122:123], 0.5, v[186:187] op_sel_hi:[1,0,1]
	global_store_dwordx4 v161, v[122:125], s[14:15] offset:64
	v_cvt_pk_bf16_f32 v244, v122, v123
	v_cvt_pk_bf16_f32 v245, v124, v125
	global_store_dwordx2 v166, v[244:245], s[20:21] offset:32
	v_mul_f32_e32 v169, v123, v123
	v_mul_f32_e32 v143, v122, v122
	v_mul_f32_e32 v145, v124, v124
	v_mul_f32_e32 v142, v125, v125
	v_add_f32_e32 v169, v169, v143
	v_add_f32_e32 v240, v145, v142
	v_add_f32_e32 v169, v169, v240
	v_add_f32_e32 v167, v167, v169
	v_pk_fma_f32 v[96:97], v[96:97], 0.5, v[192:193] op_sel_hi:[1,0,1]
	v_pk_fma_f32 v[94:95], v[94:95], 0.5, v[190:191] op_sel_hi:[1,0,1]
	global_store_dwordx4 v161, v[94:97], s[14:15] offset:512
	v_cvt_pk_bf16_f32 v244, v94, v95
	v_cvt_pk_bf16_f32 v245, v96, v97
	global_store_dwordx2 v166, v[244:245], s[20:21] offset:256
	v_mul_f32_e32 v169, v95, v95
	v_mul_f32_e32 v143, v94, v94
	v_mul_f32_e32 v145, v96, v96
	v_mul_f32_e32 v142, v97, v97
	v_add_f32_e32 v169, v169, v143
	v_add_f32_e32 v240, v145, v142
	v_add_f32_e32 v169, v169, v240
	v_add_f32_e32 v167, v167, v169
	v_pk_fma_f32 v[92:93], v[92:93], 0.5, v[196:197] op_sel_hi:[1,0,1]
	v_pk_fma_f32 v[90:91], v[90:91], 0.5, v[194:195] op_sel_hi:[1,0,1]
	global_store_dwordx4 v161, v[90:93], s[14:15] offset:576
	v_cvt_pk_bf16_f32 v244, v90, v91
	v_cvt_pk_bf16_f32 v245, v92, v93
	global_store_dwordx2 v166, v[244:245], s[20:21] offset:288
	v_mul_f32_e32 v169, v91, v91
	v_mul_f32_e32 v143, v90, v90
	v_mul_f32_e32 v145, v92, v92
	v_mul_f32_e32 v142, v93, v93
	v_add_f32_e32 v169, v169, v143
	v_add_f32_e32 v240, v145, v142
	v_add_f32_e32 v169, v169, v240
	v_add_f32_e32 v167, v167, v169
	v_add_u32_e32 v241, 0x100000, v159
	global_load_dwordx4 v[182:185], v241, s[14:15] nt
	global_load_dwordx4 v[186:189], v241, s[14:15] offset:64 nt
	global_load_dwordx4 v[190:193], v241, s[14:15] offset:512 nt
	global_load_dwordx4 v[194:197], v241, s[14:15] offset:576 nt
	v_mov_b32_e32 v168, v167
	s_nop 1
	v_permlane16_swap_b32 v167, v168
	s_nop 1
	v_add_f32_e32 v167, v167, v168
	v_mov_b32_e32 v168, v167
	s_nop 1
	v_permlane32_swap_b32 v168, v167
	v_mov_b32_e32 v242, v160
	s_and_saveexec_b64 s[10:11], vcc
	v_add_f32_e32 v243, v168, v167
	global_store_dword v242, v243, s[22:23]
	s_or_b64 exec, exec, s[10:11]
	v_add_u32_e32 v161, 0x20000, v159
	v_lshrrev_b32_e32 v166, 1, v161
	s_waitcnt vmcnt(21)
; __device__ __forceinline__ unsigned cvt_pk_bf16(float lo, float hi) { unsigned r; asm volatile("v_cvt_pk_bf16_f32 %0, %1, %2" : "=v"(r) : "v"(lo), "v"(hi)); return r; }
;     __device__ __forceinline__ void operator()(const f32x4 (&acc)[2][2][4][2], const Unit& u, int wr, int wc, int fr, int fq) const {
;     ...
;         for (int ai = 0; ai < 2; ++ai)
; #pragma unroll
;             for (int m = 0; m < 4; ++m) { const int row = u.pm * BM + ai * HALF + wr * 64 + m * 16 + fr; const int b = row >= 4224 ? 1 : 0, t = row - b * 4224; float ss = 0.f;
; #pragma unroll
;                 for (int bj = 0; bj < 2; ++bj)
; #pragma unroll
;                     for (int n = 0; n < 2; ++n) { const int col = u.pn * BM + bj * HALF + wc * 32 + n * 16 + 4 * fq; float* p = H + (size_t)row * 2048 + col;
;                         const f32x4 v = *(const f32x4*)p + acc[ai][bj][m][n] * s; *(f32x4*)p = v;
;                         if (SSQ != nullptr) { typedef unsigned u32x2 __attribute__((ext_vector_type(2))); u32x2 w; w.x = cvt_pk_bf16(v[0], v[1]); w.y = cvt_pk_bf16(v[2], v[3]); *(u32x2*)(HB + (size_t)row * 2048 + col) = w;
;                             ss += (v[0] * v[0] + v[1] * v[1]) + (v[2] * v[2] + v[3] * v[3]); }
;                         if (OUT != 0ull && t >= 128) *(__attribute__((address_space(1))) f32x4*)(OUT + ((size_t)(b * 4096 + t - 128) * 2048 + col) * 4) = v; }
;                 if (SSQ != nullptr) {
;                     { float p0 = ss, p1 = ss; asm("s_nop 1\n\tv_permlane16_swap_b32 %0, %1" : "+v"(p0), "+v"(p1)); ss = p0 + p1; p0 = ss; p1 = ss; asm("s_nop 1\n\tv_permlane32_swap_b32 %0, %1" : "+v"(p0), "+v"(p1)); ss = p0 + p1; }
;                     if (fq == 0) SSQ[(size_t)row * 32 + 4 * u.pn + wc] = ss; }
;                 asm volatile("" ::: "memory"); }
	v_pk_fma_f32 v[120:121], v[120:121], 0.5, v[200:201] op_sel_hi:[1,0,1]
	v_pk_fma_f32 v[118:119], v[118:119], 0.5, v[198:199] op_sel_hi:[1,0,1]
	global_store_dwordx4 v161, v[118:121], s[14:15]
	v_cvt_pk_bf16_f32 v244, v118, v119
	v_cvt_pk_bf16_f32 v245, v120, v121
	global_store_dwordx2 v166, v[244:245], s[20:21]
	v_mul_f32_e32 v167, v119, v119
	v_mul_f32_e32 v143, v118, v118
	v_mul_f32_e32 v145, v120, v120
	v_mul_f32_e32 v142, v121, v121
	v_add_f32_e32 v167, v167, v143
	v_add_f32_e32 v240, v145, v142
	v_add_f32_e32 v167, v167, v240
	v_pk_fma_f32 v[116:117], v[116:117], 0.5, v[204:205] op_sel_hi:[1,0,1]
	v_pk_fma_f32 v[114:115], v[114:115], 0.5, v[202:203] op_sel_hi:[1,0,1]
	global_store_dwordx4 v161, v[114:117], s[14:15] offset:64
	v_cvt_pk_bf16_f32 v244, v114, v115
	v_cvt_pk_bf16_f32 v245, v116, v117
	global_store_dwordx2 v166, v[244:245], s[20:21] offset:32
	v_mul_f32_e32 v169, v115, v115
	v_mul_f32_e32 v143, v114, v114
	v_mul_f32_e32 v145, v116, v116
	v_mul_f32_e32 v142, v117, v117
	v_add_f32_e32 v169, v169, v143
	v_add_f32_e32 v240, v145, v142
	v_add_f32_e32 v169, v169, v240
	v_add_f32_e32 v167, v167, v169
	v_pk_fma_f32 v[88:89], v[88:89], 0.5, v[208:209] op_sel_hi:[1,0,1]
	v_pk_fma_f32 v[86:87], v[86:87], 0.5, v[206:207] op_sel_hi:[1,0,1]
	global_store_dwordx4 v161, v[86:89], s[14:15] offset:512
	v_cvt_pk_bf16_f32 v244, v86, v87
	v_cvt_pk_bf16_f32 v245, v88, v89
	global_store_dwordx2 v166, v[244:245], s[20:21] offset:256
	v_mul_f32_e32 v169, v87, v87
	v_mul_f32_e32 v143, v86, v86
	v_mul_f32_e32 v145, v88, v88
	v_mul_f32_e32 v142, v89, v89
	v_add_f32_e32 v169, v169, v143
	v_add_f32_e32 v240, v145, v142
	v_add_f32_e32 v169, v169, v240
	v_add_f32_e32 v167, v167, v169
	v_pk_fma_f32 v[84:85], v[84:85], 0.5, v[212:213] op_sel_hi:[1,0,1]
	v_pk_fma_f32 v[82:83], v[82:83], 0.5, v[210:211] op_sel_hi:[1,0,1]
	global_store_dwordx4 v161, v[82:85], s[14:15] offset:576
	v_cvt_pk_bf16_f32 v244, v82, v83
	v_cvt_pk_bf16_f32 v245, v84, v85
	global_store_dwordx2 v166, v[244:245], s[20:21] offset:288
	v_mul_f32_e32 v169, v83, v83
	v_mul_f32_e32 v143, v82, v82
	v_mul_f32_e32 v145, v84, v84
	v_mul_f32_e32 v142, v85, v85
	v_add_f32_e32 v169, v169, v143
	v_add_f32_e32 v240, v145, v142
	v_add_f32_e32 v169, v169, v240
	v_add_f32_e32 v167, v167, v169
	v_add_u32_e32 v241, 0x120000, v159
	global_load_dwordx4 v[198:201], v241, s[14:15] nt
	global_load_dwordx4 v[202:205], v241, s[14:15] offset:64 nt
	global_load_dwordx4 v[206:209], v241, s[14:15] offset:512 nt
	global_load_dwordx4 v[210:213], v241, s[14:15] offset:576 nt
	v_mov_b32_e32 v168, v167
	s_nop 1
	v_permlane16_swap_b32 v167, v168
	s_nop 1
	v_add_f32_e32 v167, v167, v168
	v_mov_b32_e32 v168, v167
	s_nop 1
	v_permlane32_swap_b32 v168, v167
	v_add_u32_e32 v242, 0x800, v160
	s_and_saveexec_b64 s[10:11], vcc
	v_add_f32_e32 v243, v168, v167
	global_store_dword v242, v243, s[22:23]
	s_or_b64 exec, exec, s[10:11]
	v_add_u32_e32 v161, 0x40000, v159
	v_lshrrev_b32_e32 v166, 1, v161
	s_waitcnt vmcnt(30)
	v_pk_fma_f32 v[112:113], v[112:113], 0.5, v[216:217] op_sel_hi:[1,0,1]
	v_pk_fma_f32 v[110:111], v[110:111], 0.5, v[214:215] op_sel_hi:[1,0,1]
	global_store_dwordx4 v161, v[110:113], s[14:15]
	v_cvt_pk_bf16_f32 v244, v110, v111
	v_cvt_pk_bf16_f32 v245, v112, v113
	global_store_dwordx2 v166, v[244:245], s[20:21]
	v_mul_f32_e32 v167, v111, v111
	v_mul_f32_e32 v143, v110, v110
	v_mul_f32_e32 v145, v112, v112
	v_mul_f32_e32 v142, v113, v113
	v_add_f32_e32 v167, v167, v143
	v_add_f32_e32 v240, v145, v142
	v_add_f32_e32 v167, v167, v240
	v_pk_fma_f32 v[108:109], v[108:109], 0.5, v[220:221] op_sel_hi:[1,0,1]
	v_pk_fma_f32 v[106:107], v[106:107], 0.5, v[218:219] op_sel_hi:[1,0,1]
	global_store_dwordx4 v161, v[106:109], s[14:15] offset:64
	v_cvt_pk_bf16_f32 v244, v106, v107
	v_cvt_pk_bf16_f32 v245, v108, v109
	global_store_dwordx2 v166, v[244:245], s[20:21] offset:32
	v_mul_f32_e32 v169, v107, v107
	v_mul_f32_e32 v143, v106, v106
	v_mul_f32_e32 v145, v108, v108
	v_mul_f32_e32 v142, v109, v109
	v_add_f32_e32 v169, v169, v143
	v_add_f32_e32 v240, v145, v142
	v_add_f32_e32 v169, v169, v240
	v_add_f32_e32 v167, v167, v169
	v_pk_fma_f32 v[80:81], v[80:81], 0.5, v[224:225] op_sel_hi:[1,0,1]
	v_pk_fma_f32 v[78:79], v[78:79], 0.5, v[222:223] op_sel_hi:[1,0,1]
	global_store_dwordx4 v161, v[78:81], s[14:15] offset:512
	v_cvt_pk_bf16_f32 v244, v78, v79
	v_cvt_pk_bf16_f32 v245, v80, v81
	global_store_dwordx2 v166, v[244:245], s[20:21] offset:256
	v_mul_f32_e32 v169, v79, v79
	v_mul_f32_e32 v143, v78, v78
	v_mul_f32_e32 v145, v80, v80
	v_mul_f32_e32 v142, v81, v81
	v_add_f32_e32 v169, v169, v143
	v_add_f32_e32 v240, v145, v142
	v_add_f32_e32 v169, v169, v240
	v_add_f32_e32 v167, v167, v169
	v_pk_fma_f32 v[76:77], v[76:77], 0.5, v[228:229] op_sel_hi:[1,0,1]
	v_pk_fma_f32 v[74:75], v[74:75], 0.5, v[226:227] op_sel_hi:[1,0,1]
	global_store_dwordx4 v161, v[74:77], s[14:15] offset:576
	v_cvt_pk_bf16_f32 v244, v74, v75
	v_cvt_pk_bf16_f32 v245, v76, v77
	global_store_dwordx2 v166, v[244:245], s[20:21] offset:288
	v_mul_f32_e32 v169, v75, v75
	v_mul_f32_e32 v143, v74, v74
	v_mul_f32_e32 v145, v76, v76
	v_mul_f32_e32 v142, v77, v77
	v_add_f32_e32 v169, v169, v143
	v_add_f32_e32 v240, v145, v142
	v_add_f32_e32 v169, v169, v240
	v_add_f32_e32 v167, v167, v169
	v_add_u32_e32 v241, 0x140000, v159
	global_load_dwordx4 v[214:217], v241, s[14:15] nt
	global_load_dwordx4 v[218:221], v241, s[14:15] offset:64 nt
	global_load_dwordx4 v[222:225], v241, s[14:15] offset:512 nt
	global_load_dwordx4 v[226:229], v241, s[14:15] offset:576 nt
	v_mov_b32_e32 v168, v167
	s_nop 1
	v_permlane16_swap_b32 v167, v168
	s_nop 1
	v_add_f32_e32 v167, v167, v168
	v_mov_b32_e32 v168, v167
	s_nop 1
	v_permlane32_swap_b32 v168, v167
	v_add_u32_e32 v242, 0x1000, v160
	s_and_saveexec_b64 s[10:11], vcc
	v_add_f32_e32 v243, v168, v167
	global_store_dword v242, v243, s[22:23]
	s_or_b64 exec, exec, s[10:11]
	v_add_u32_e32 v161, 0x60000, v159
	v_lshrrev_b32_e32 v166, 1, v161
	s_waitcnt vmcnt(39)
; __device__ __forceinline__ unsigned cvt_pk_bf16(float lo, float hi) { unsigned r; asm volatile("v_cvt_pk_bf16_f32 %0, %1, %2" : "=v"(r) : "v"(lo), "v"(hi)); return r; }
;     __device__ __forceinline__ void operator()(const f32x4 (&acc)[2][2][4][2], const Unit& u, int wr, int wc, int fr, int fq) const {
;     ...
;         for (int ai = 0; ai < 2; ++ai)
; #pragma unroll
;             for (int m = 0; m < 4; ++m) { const int row = u.pm * BM + ai * HALF + wr * 64 + m * 16 + fr; const int b = row >= 4224 ? 1 : 0, t = row - b * 4224; float ss = 0.f;
; #pragma unroll
;                 for (int bj = 0; bj < 2; ++bj)
; #pragma unroll
;                     for (int n = 0; n < 2; ++n) { const int col = u.pn * BM + bj * HALF + wc * 32 + n * 16 + 4 * fq; float* p = H + (size_t)row * 2048 + col;
;                         const f32x4 v = *(const f32x4*)p + acc[ai][bj][m][n] * s; *(f32x4*)p = v;
;                         if (SSQ != nullptr) { typedef unsigned u32x2 __attribute__((ext_vector_type(2))); u32x2 w; w.x = cvt_pk_bf16(v[0], v[1]); w.y = cvt_pk_bf16(v[2], v[3]); *(u32x2*)(HB + (size_t)row * 2048 + col) = w;
;                             ss += (v[0] * v[0] + v[1] * v[1]) + (v[2] * v[2] + v[3] * v[3]); }
;                         if (OUT != 0ull && t >= 128) *(__attribute__((address_space(1))) f32x4*)(OUT + ((size_t)(b * 4096 + t - 128) * 2048 + col) * 4) = v; }
;                 if (SSQ != nullptr) {
;                     { float p0 = ss, p1 = ss; asm("s_nop 1\n\tv_permlane16_swap_b32 %0, %1" : "+v"(p0), "+v"(p1)); ss = p0 + p1; p0 = ss; p1 = ss; asm("s_nop 1\n\tv_permlane32_swap_b32 %0, %1" : "+v"(p0), "+v"(p1)); ss = p0 + p1; }
;                     if (fq == 0) SSQ[(size_t)row * 32 + 4 * u.pn + wc] = ss; }
;                 asm volatile("" ::: "memory"); }
	v_pk_fma_f32 v[104:105], v[104:105], 0.5, v[148:149] op_sel_hi:[1,0,1]
	v_pk_fma_f32 v[102:103], v[102:103], 0.5, v[146:147] op_sel_hi:[1,0,1]
	global_store_dwordx4 v161, v[102:105], s[14:15]
	v_cvt_pk_bf16_f32 v244, v102, v103
	v_cvt_pk_bf16_f32 v245, v104, v105
	global_store_dwordx2 v166, v[244:245], s[20:21]
	v_mul_f32_e32 v167, v103, v103
	v_mul_f32_e32 v143, v102, v102
	v_mul_f32_e32 v145, v104, v104
	v_mul_f32_e32 v142, v105, v105
	v_add_f32_e32 v167, v167, v143
	v_add_f32_e32 v240, v145, v142
	v_add_f32_e32 v167, v167, v240
	v_pk_fma_f32 v[100:101], v[100:101], 0.5, v[152:153] op_sel_hi:[1,0,1]
	v_pk_fma_f32 v[98:99], v[98:99], 0.5, v[150:151] op_sel_hi:[1,0,1]
	global_store_dwordx4 v161, v[98:101], s[14:15] offset:64
	v_cvt_pk_bf16_f32 v244, v98, v99
	v_cvt_pk_bf16_f32 v245, v100, v101
	global_store_dwordx2 v166, v[244:245], s[20:21] offset:32
	v_mul_f32_e32 v169, v99, v99
	v_mul_f32_e32 v143, v98, v98
	v_mul_f32_e32 v145, v100, v100
	v_mul_f32_e32 v142, v101, v101
	v_add_f32_e32 v169, v169, v143
	v_add_f32_e32 v240, v145, v142
	v_add_f32_e32 v169, v169, v240
	v_add_f32_e32 v167, v167, v169
	v_pk_fma_f32 v[72:73], v[72:73], 0.5, v[156:157] op_sel_hi:[1,0,1]
	v_pk_fma_f32 v[70:71], v[70:71], 0.5, v[154:155] op_sel_hi:[1,0,1]
	global_store_dwordx4 v161, v[70:73], s[14:15] offset:512
	v_cvt_pk_bf16_f32 v244, v70, v71
	v_cvt_pk_bf16_f32 v245, v72, v73
	global_store_dwordx2 v166, v[244:245], s[20:21] offset:256
	v_mul_f32_e32 v169, v71, v71
	v_mul_f32_e32 v143, v70, v70
	v_mul_f32_e32 v145, v72, v72
	v_mul_f32_e32 v142, v73, v73
	v_add_f32_e32 v169, v169, v143
	v_add_f32_e32 v240, v145, v142
	v_add_f32_e32 v169, v169, v240
	v_add_f32_e32 v167, v167, v169
	v_pk_fma_f32 v[68:69], v[68:69], 0.5, v[132:133] op_sel_hi:[1,0,1]
	v_pk_fma_f32 v[66:67], v[66:67], 0.5, v[130:131] op_sel_hi:[1,0,1]
	global_store_dwordx4 v161, v[66:69], s[14:15] offset:576
	v_cvt_pk_bf16_f32 v244, v66, v67
	v_cvt_pk_bf16_f32 v245, v68, v69
	global_store_dwordx2 v166, v[244:245], s[20:21] offset:288
	v_mul_f32_e32 v169, v67, v67
	v_mul_f32_e32 v143, v66, v66
	v_mul_f32_e32 v145, v68, v68
	v_mul_f32_e32 v142, v69, v69
	v_add_f32_e32 v169, v169, v143
	v_add_f32_e32 v240, v145, v142
	v_add_f32_e32 v169, v169, v240
	v_add_f32_e32 v167, v167, v169
	v_add_u32_e32 v241, 0x160000, v159
	global_load_dwordx4 v[146:149], v241, s[14:15] nt
	global_load_dwordx4 v[150:153], v241, s[14:15] offset:64 nt
	global_load_dwordx4 v[154:157], v241, s[14:15] offset:512 nt
	global_load_dwordx4 v[130:133], v241, s[14:15] offset:576 nt
	v_mov_b32_e32 v168, v167
	s_nop 1
	v_permlane16_swap_b32 v167, v168
	s_nop 1
	v_add_f32_e32 v167, v167, v168
	v_mov_b32_e32 v168, v167
	s_nop 1
	v_permlane32_swap_b32 v168, v167
	v_add_u32_e32 v242, 0x1800, v160
	s_and_saveexec_b64 s[10:11], vcc
	v_add_f32_e32 v243, v168, v167
	global_store_dword v242, v243, s[22:23]
	s_or_b64 exec, exec, s[10:11]
	v_add_u32_e32 v161, 0x100000, v159
	v_lshrrev_b32_e32 v166, 1, v161
	s_waitcnt vmcnt(40)
	v_pk_fma_f32 v[64:65], v[64:65], 0.5, v[184:185] op_sel_hi:[1,0,1]
	v_pk_fma_f32 v[62:63], v[62:63], 0.5, v[182:183] op_sel_hi:[1,0,1]
	global_store_dwordx4 v161, v[62:65], s[14:15]
	v_cvt_pk_bf16_f32 v244, v62, v63
	v_cvt_pk_bf16_f32 v245, v64, v65
	global_store_dwordx2 v166, v[244:245], s[20:21]
	v_mul_f32_e32 v167, v63, v63
	v_mul_f32_e32 v143, v62, v62
	v_mul_f32_e32 v145, v64, v64
	v_mul_f32_e32 v142, v65, v65
	v_add_f32_e32 v167, v167, v143
	v_add_f32_e32 v240, v145, v142
	v_add_f32_e32 v167, v167, v240
	v_pk_fma_f32 v[60:61], v[60:61], 0.5, v[188:189] op_sel_hi:[1,0,1]
	v_pk_fma_f32 v[58:59], v[58:59], 0.5, v[186:187] op_sel_hi:[1,0,1]
	global_store_dwordx4 v161, v[58:61], s[14:15] offset:64
	v_cvt_pk_bf16_f32 v244, v58, v59
	v_cvt_pk_bf16_f32 v245, v60, v61
	global_store_dwordx2 v166, v[244:245], s[20:21] offset:32
	v_mul_f32_e32 v169, v59, v59
	v_mul_f32_e32 v143, v58, v58
	v_mul_f32_e32 v145, v60, v60
	v_mul_f32_e32 v142, v61, v61
	v_add_f32_e32 v169, v169, v143
	v_add_f32_e32 v240, v145, v142
	v_add_f32_e32 v169, v169, v240
	v_add_f32_e32 v167, v167, v169
	v_pk_fma_f32 v[32:33], v[32:33], 0.5, v[192:193] op_sel_hi:[1,0,1]
	v_pk_fma_f32 v[30:31], v[30:31], 0.5, v[190:191] op_sel_hi:[1,0,1]
	global_store_dwordx4 v161, v[30:33], s[14:15] offset:512
	v_cvt_pk_bf16_f32 v244, v30, v31
	v_cvt_pk_bf16_f32 v245, v32, v33
	global_store_dwordx2 v166, v[244:245], s[20:21] offset:256
	v_mul_f32_e32 v169, v31, v31
	v_mul_f32_e32 v143, v30, v30
	v_mul_f32_e32 v145, v32, v32
	v_mul_f32_e32 v142, v33, v33
	v_add_f32_e32 v169, v169, v143
	v_add_f32_e32 v240, v145, v142
	v_add_f32_e32 v169, v169, v240
	v_add_f32_e32 v167, v167, v169
	v_pk_fma_f32 v[28:29], v[28:29], 0.5, v[196:197] op_sel_hi:[1,0,1]
	v_pk_fma_f32 v[26:27], v[26:27], 0.5, v[194:195] op_sel_hi:[1,0,1]
	global_store_dwordx4 v161, v[26:29], s[14:15] offset:576
	v_cvt_pk_bf16_f32 v244, v26, v27
	v_cvt_pk_bf16_f32 v245, v28, v29
	global_store_dwordx2 v166, v[244:245], s[20:21] offset:288
	v_mul_f32_e32 v169, v27, v27
	v_mul_f32_e32 v143, v26, v26
	v_mul_f32_e32 v145, v28, v28
	v_mul_f32_e32 v142, v29, v29
	v_add_f32_e32 v169, v169, v143
	v_add_f32_e32 v240, v145, v142
	v_add_f32_e32 v169, v169, v240
	v_add_f32_e32 v167, v167, v169
	v_mov_b32_e32 v168, v167
	s_nop 1
	v_permlane16_swap_b32 v167, v168
	s_nop 1
	v_add_f32_e32 v167, v167, v168
	v_mov_b32_e32 v168, v167
	s_nop 1
	v_permlane32_swap_b32 v168, v167
	v_add_u32_e32 v242, 0x4000, v160
	s_and_saveexec_b64 s[10:11], vcc
	v_add_f32_e32 v243, v168, v167
	global_store_dword v242, v243, s[22:23]
	s_or_b64 exec, exec, s[10:11]
	v_add_u32_e32 v161, 0x120000, v159
	v_lshrrev_b32_e32 v166, 1, v161
	s_waitcnt vmcnt(36)
; __device__ __forceinline__ unsigned cvt_pk_bf16(float lo, float hi) { unsigned r; asm volatile("v_cvt_pk_bf16_f32 %0, %1, %2" : "=v"(r) : "v"(lo), "v"(hi)); return r; }
;     __device__ __forceinline__ void operator()(const f32x4 (&acc)[2][2][4][2], const Unit& u, int wr, int wc, int fr, int fq) const {
;     ...
;         for (int ai = 0; ai < 2; ++ai)
; #pragma unroll
;             for (int m = 0; m < 4; ++m) { const int row = u.pm * BM + ai * HALF + wr * 64 + m * 16 + fr; const int b = row >= 4224 ? 1 : 0, t = row - b * 4224; float ss = 0.f;
; #pragma unroll
;                 for (int bj = 0; bj < 2; ++bj)
; #pragma unroll
;                     for (int n = 0; n < 2; ++n) { const int col = u.pn * BM + bj * HALF + wc * 32 + n * 16 + 4 * fq; float* p = H + (size_t)row * 2048 + col;
;                         const f32x4 v = *(const f32x4*)p + acc[ai][bj][m][n] * s; *(f32x4*)p = v;
;                         if (SSQ != nullptr) { typedef unsigned u32x2 __attribute__((ext_vector_type(2))); u32x2 w; w.x = cvt_pk_bf16(v[0], v[1]); w.y = cvt_pk_bf16(v[2], v[3]); *(u32x2*)(HB + (size_t)row * 2048 + col) = w;
;                             ss += (v[0] * v[0] + v[1] * v[1]) + (v[2] * v[2] + v[3] * v[3]); }
;                         if (OUT != 0ull && t >= 128) *(__attribute__((address_space(1))) f32x4*)(OUT + ((size_t)(b * 4096 + t - 128) * 2048 + col) * 4) = v; }
;                 if (SSQ != nullptr) {
;                     { float p0 = ss, p1 = ss; asm("s_nop 1\n\tv_permlane16_swap_b32 %0, %1" : "+v"(p0), "+v"(p1)); ss = p0 + p1; p0 = ss; p1 = ss; asm("s_nop 1\n\tv_permlane32_swap_b32 %0, %1" : "+v"(p0), "+v"(p1)); ss = p0 + p1; }
;                     if (fq == 0) SSQ[(size_t)row * 32 + 4 * u.pn + wc] = ss; }
;                 asm volatile("" ::: "memory"); }
	v_pk_fma_f32 v[56:57], v[56:57], 0.5, v[200:201] op_sel_hi:[1,0,1]
	v_pk_fma_f32 v[54:55], v[54:55], 0.5, v[198:199] op_sel_hi:[1,0,1]
	global_store_dwordx4 v161, v[54:57], s[14:15]
	v_cvt_pk_bf16_f32 v244, v54, v55
	v_cvt_pk_bf16_f32 v245, v56, v57
	global_store_dwordx2 v166, v[244:245], s[20:21]
	v_mul_f32_e32 v167, v55, v55
	v_mul_f32_e32 v143, v54, v54
	v_mul_f32_e32 v145, v56, v56
	v_mul_f32_e32 v142, v57, v57
	v_add_f32_e32 v167, v167, v143
	v_add_f32_e32 v240, v145, v142
	v_add_f32_e32 v167, v167, v240
	v_pk_fma_f32 v[52:53], v[52:53], 0.5, v[204:205] op_sel_hi:[1,0,1]
	v_pk_fma_f32 v[50:51], v[50:51], 0.5, v[202:203] op_sel_hi:[1,0,1]
	global_store_dwordx4 v161, v[50:53], s[14:15] offset:64
	v_cvt_pk_bf16_f32 v244, v50, v51
	v_cvt_pk_bf16_f32 v245, v52, v53
	global_store_dwordx2 v166, v[244:245], s[20:21] offset:32
	v_mul_f32_e32 v169, v51, v51
	v_mul_f32_e32 v143, v50, v50
	v_mul_f32_e32 v145, v52, v52
	v_mul_f32_e32 v142, v53, v53
	v_add_f32_e32 v169, v169, v143
	v_add_f32_e32 v240, v145, v142
	v_add_f32_e32 v169, v169, v240
	v_add_f32_e32 v167, v167, v169
	v_pk_fma_f32 v[24:25], v[24:25], 0.5, v[208:209] op_sel_hi:[1,0,1]
	v_pk_fma_f32 v[22:23], v[22:23], 0.5, v[206:207] op_sel_hi:[1,0,1]
	global_store_dwordx4 v161, v[22:25], s[14:15] offset:512
	v_cvt_pk_bf16_f32 v244, v22, v23
	v_cvt_pk_bf16_f32 v245, v24, v25
	global_store_dwordx2 v166, v[244:245], s[20:21] offset:256
	v_mul_f32_e32 v169, v23, v23
	v_mul_f32_e32 v143, v22, v22
	v_mul_f32_e32 v145, v24, v24
	v_mul_f32_e32 v142, v25, v25
	v_add_f32_e32 v169, v169, v143
	v_add_f32_e32 v240, v145, v142
	v_add_f32_e32 v169, v169, v240
	v_add_f32_e32 v167, v167, v169
	v_pk_fma_f32 v[20:21], v[20:21], 0.5, v[212:213] op_sel_hi:[1,0,1]
	v_pk_fma_f32 v[18:19], v[18:19], 0.5, v[210:211] op_sel_hi:[1,0,1]
	global_store_dwordx4 v161, v[18:21], s[14:15] offset:576
	v_cvt_pk_bf16_f32 v244, v18, v19
	v_cvt_pk_bf16_f32 v245, v20, v21
	global_store_dwordx2 v166, v[244:245], s[20:21] offset:288
	v_mul_f32_e32 v169, v19, v19
	v_mul_f32_e32 v143, v18, v18
	v_mul_f32_e32 v145, v20, v20
	v_mul_f32_e32 v142, v21, v21
	v_add_f32_e32 v169, v169, v143
	v_add_f32_e32 v240, v145, v142
	v_add_f32_e32 v169, v169, v240
	v_add_f32_e32 v167, v167, v169
	v_mov_b32_e32 v168, v167
	s_nop 1
	v_permlane16_swap_b32 v167, v168
	s_nop 1
	v_add_f32_e32 v167, v167, v168
	v_mov_b32_e32 v168, v167
	s_nop 1
	v_permlane32_swap_b32 v168, v167
	v_add_u32_e32 v242, 0x4800, v160
	s_and_saveexec_b64 s[10:11], vcc
	v_add_f32_e32 v243, v168, v167
	global_store_dword v242, v243, s[22:23]
	s_or_b64 exec, exec, s[10:11]
	v_add_u32_e32 v161, 0x140000, v159
	v_lshrrev_b32_e32 v166, 1, v161
	s_waitcnt vmcnt(32)
; __device__ __forceinline__ unsigned cvt_pk_bf16(float lo, float hi) { unsigned r; asm volatile("v_cvt_pk_bf16_f32 %0, %1, %2" : "=v"(r) : "v"(lo), "v"(hi)); return r; }
;     __device__ __forceinline__ void operator()(const f32x4 (&acc)[2][2][4][2], const Unit& u, int wr, int wc, int fr, int fq) const {
;     ...
;         for (int ai = 0; ai < 2; ++ai)
; #pragma unroll
;             for (int m = 0; m < 4; ++m) { const int row = u.pm * BM + ai * HALF + wr * 64 + m * 16 + fr; const int b = row >= 4224 ? 1 : 0, t = row - b * 4224; float ss = 0.f;
; #pragma unroll
;                 for (int bj = 0; bj < 2; ++bj)
; #pragma unroll
;                     for (int n = 0; n < 2; ++n) { const int col = u.pn * BM + bj * HALF + wc * 32 + n * 16 + 4 * fq; float* p = H + (size_t)row * 2048 + col;
;                         const f32x4 v = *(const f32x4*)p + acc[ai][bj][m][n] * s; *(f32x4*)p = v;
;                         if (SSQ != nullptr) { typedef unsigned u32x2 __attribute__((ext_vector_type(2))); u32x2 w; w.x = cvt_pk_bf16(v[0], v[1]); w.y = cvt_pk_bf16(v[2], v[3]); *(u32x2*)(HB + (size_t)row * 2048 + col) = w;
;                             ss += (v[0] * v[0] + v[1] * v[1]) + (v[2] * v[2] + v[3] * v[3]); }
;                         if (OUT != 0ull && t >= 128) *(__attribute__((address_space(1))) f32x4*)(OUT + ((size_t)(b * 4096 + t - 128) * 2048 + col) * 4) = v; }
;                 if (SSQ != nullptr) {
;                     { float p0 = ss, p1 = ss; asm("s_nop 1\n\tv_permlane16_swap_b32 %0, %1" : "+v"(p0), "+v"(p1)); ss = p0 + p1; p0 = ss; p1 = ss; asm("s_nop 1\n\tv_permlane32_swap_b32 %0, %1" : "+v"(p0), "+v"(p1)); ss = p0 + p1; }
;                     if (fq == 0) SSQ[(size_t)row * 32 + 4 * u.pn + wc] = ss; }
;                 asm volatile("" ::: "memory"); }
	v_pk_fma_f32 v[48:49], v[48:49], 0.5, v[216:217] op_sel_hi:[1,0,1]
	v_pk_fma_f32 v[46:47], v[46:47], 0.5, v[214:215] op_sel_hi:[1,0,1]
	global_store_dwordx4 v161, v[46:49], s[14:15]
	v_cvt_pk_bf16_f32 v244, v46, v47
	v_cvt_pk_bf16_f32 v245, v48, v49
	global_store_dwordx2 v166, v[244:245], s[20:21]
	v_mul_f32_e32 v167, v47, v47
	v_mul_f32_e32 v143, v46, v46
	v_mul_f32_e32 v145, v48, v48
	v_mul_f32_e32 v142, v49, v49
	v_add_f32_e32 v167, v167, v143
	v_add_f32_e32 v240, v145, v142
	v_add_f32_e32 v167, v167, v240
	v_pk_fma_f32 v[44:45], v[44:45], 0.5, v[220:221] op_sel_hi:[1,0,1]
	v_pk_fma_f32 v[42:43], v[42:43], 0.5, v[218:219] op_sel_hi:[1,0,1]
	global_store_dwordx4 v161, v[42:45], s[14:15] offset:64
	v_cvt_pk_bf16_f32 v244, v42, v43
	v_cvt_pk_bf16_f32 v245, v44, v45
	global_store_dwordx2 v166, v[244:245], s[20:21] offset:32
	v_mul_f32_e32 v169, v43, v43
	v_mul_f32_e32 v143, v42, v42
	v_mul_f32_e32 v145, v44, v44
	v_mul_f32_e32 v142, v45, v45
	v_add_f32_e32 v169, v169, v143
	v_add_f32_e32 v240, v145, v142
	v_add_f32_e32 v169, v169, v240
	v_add_f32_e32 v167, v167, v169
	v_pk_fma_f32 v[16:17], v[16:17], 0.5, v[224:225] op_sel_hi:[1,0,1]
	v_pk_fma_f32 v[14:15], v[14:15], 0.5, v[222:223] op_sel_hi:[1,0,1]
	global_store_dwordx4 v161, v[14:17], s[14:15] offset:512
	v_cvt_pk_bf16_f32 v244, v14, v15
	v_cvt_pk_bf16_f32 v245, v16, v17
	global_store_dwordx2 v166, v[244:245], s[20:21] offset:256
	v_mul_f32_e32 v169, v15, v15
	v_mul_f32_e32 v143, v14, v14
	v_mul_f32_e32 v145, v16, v16
	v_mul_f32_e32 v142, v17, v17
	v_add_f32_e32 v169, v169, v143
	v_add_f32_e32 v240, v145, v142
	v_add_f32_e32 v169, v169, v240
	v_add_f32_e32 v167, v167, v169
	v_pk_fma_f32 v[12:13], v[12:13], 0.5, v[228:229] op_sel_hi:[1,0,1]
	v_pk_fma_f32 v[10:11], v[10:11], 0.5, v[226:227] op_sel_hi:[1,0,1]
	global_store_dwordx4 v161, v[10:13], s[14:15] offset:576
	v_cvt_pk_bf16_f32 v244, v10, v11
	v_cvt_pk_bf16_f32 v245, v12, v13
	global_store_dwordx2 v166, v[244:245], s[20:21] offset:288
	v_mul_f32_e32 v169, v11, v11
	v_mul_f32_e32 v143, v10, v10
	v_mul_f32_e32 v145, v12, v12
	v_mul_f32_e32 v142, v13, v13
	v_add_f32_e32 v169, v169, v143
	v_add_f32_e32 v240, v145, v142
	v_add_f32_e32 v169, v169, v240
	v_add_f32_e32 v167, v167, v169
	v_mov_b32_e32 v168, v167
	s_nop 1
	v_permlane16_swap_b32 v167, v168
	s_nop 1
	v_add_f32_e32 v167, v167, v168
	v_mov_b32_e32 v168, v167
	s_nop 1
	v_permlane32_swap_b32 v168, v167
	v_add_u32_e32 v242, 0x5000, v160
	s_and_saveexec_b64 s[10:11], vcc
	v_add_f32_e32 v243, v168, v167
	global_store_dword v242, v243, s[22:23]
	s_or_b64 exec, exec, s[10:11]
	v_add_u32_e32 v161, 0x160000, v159
	v_lshrrev_b32_e32 v166, 1, v161
	s_waitcnt vmcnt(28)
	v_pk_fma_f32 v[40:41], v[40:41], 0.5, v[148:149] op_sel_hi:[1,0,1]
	v_pk_fma_f32 v[38:39], v[38:39], 0.5, v[146:147] op_sel_hi:[1,0,1]
	global_store_dwordx4 v161, v[38:41], s[14:15]
	v_cvt_pk_bf16_f32 v244, v38, v39
	v_cvt_pk_bf16_f32 v245, v40, v41
	global_store_dwordx2 v166, v[244:245], s[20:21]
	v_mul_f32_e32 v167, v39, v39
	v_mul_f32_e32 v143, v38, v38
	v_mul_f32_e32 v145, v40, v40
	v_mul_f32_e32 v142, v41, v41
	v_add_f32_e32 v167, v167, v143
	v_add_f32_e32 v240, v145, v142
	v_add_f32_e32 v167, v167, v240
	v_pk_fma_f32 v[36:37], v[36:37], 0.5, v[152:153] op_sel_hi:[1,0,1]
	v_pk_fma_f32 v[34:35], v[34:35], 0.5, v[150:151] op_sel_hi:[1,0,1]
	global_store_dwordx4 v161, v[34:37], s[14:15] offset:64
	v_cvt_pk_bf16_f32 v244, v34, v35
	v_cvt_pk_bf16_f32 v245, v36, v37
	global_store_dwordx2 v166, v[244:245], s[20:21] offset:32
	v_mul_f32_e32 v169, v35, v35
	v_mul_f32_e32 v143, v34, v34
	v_mul_f32_e32 v145, v36, v36
	v_mul_f32_e32 v142, v37, v37
	v_add_f32_e32 v169, v169, v143
	v_add_f32_e32 v240, v145, v142
	v_add_f32_e32 v169, v169, v240
	v_add_f32_e32 v167, v167, v169
	v_pk_fma_f32 v[8:9], v[8:9], 0.5, v[156:157] op_sel_hi:[1,0,1]
	v_pk_fma_f32 v[6:7], v[6:7], 0.5, v[154:155] op_sel_hi:[1,0,1]
	global_store_dwordx4 v161, v[6:9], s[14:15] offset:512
	v_cvt_pk_bf16_f32 v244, v6, v7
	v_cvt_pk_bf16_f32 v245, v8, v9
	global_store_dwordx2 v166, v[244:245], s[20:21] offset:256
	v_mul_f32_e32 v169, v7, v7
	v_mul_f32_e32 v143, v6, v6
	v_mul_f32_e32 v145, v8, v8
	v_mul_f32_e32 v142, v9, v9
	v_add_f32_e32 v169, v169, v143
	v_add_f32_e32 v240, v145, v142
	v_add_f32_e32 v169, v169, v240
	v_add_f32_e32 v167, v167, v169
	v_pk_fma_f32 v[4:5], v[4:5], 0.5, v[132:133] op_sel_hi:[1,0,1]
	v_pk_fma_f32 v[2:3], v[2:3], 0.5, v[130:131] op_sel_hi:[1,0,1]
	global_store_dwordx4 v161, v[2:5], s[14:15] offset:576
	v_cvt_pk_bf16_f32 v244, v2, v3
	v_cvt_pk_bf16_f32 v245, v4, v5
	global_store_dwordx2 v166, v[244:245], s[20:21] offset:288
	v_mul_f32_e32 v169, v3, v3
	v_mul_f32_e32 v143, v2, v2
	v_mul_f32_e32 v145, v4, v4
	v_mul_f32_e32 v142, v5, v5
	v_add_f32_e32 v169, v169, v143
	v_add_f32_e32 v240, v145, v142
	v_add_f32_e32 v169, v169, v240
	v_add_f32_e32 v167, v167, v169
	v_mov_b32_e32 v168, v167
	s_nop 1
	v_permlane16_swap_b32 v167, v168
	s_nop 1
	v_add_f32_e32 v167, v167, v168
	v_mov_b32_e32 v168, v167
	s_nop 1
	v_permlane32_swap_b32 v168, v167
	v_add_u32_e32 v242, 0x5800, v160
	s_and_saveexec_b64 s[10:11], vcc
	v_add_f32_e32 v243, v168, v167
	global_store_dword v242, v243, s[22:23]
	s_or_b64 exec, exec, s[10:11]
	s_branch .LBB0_1744
